# P1 gate-tile outputs (consumed two phases later) stored non-temporally so q/k/v stay cache-resident for attention; layers 1-3
# baseline (speedup 1.0000x reference)
.Le1m2_10:
	v_mov_b32_e32 v200, 0xbfb8aa3b
	v_mov_b32_e32 v201, 1.0
	s_cmp_eq_u32 s36, s69
	s_movk_i32 s0, 0x200
	s_cselect_b32 s0, s0, 0x300
	s_cmp_lg_u32 s36, s68
	v_mov_b32_e32 v198, v193
	v_mov_b32_e32 v44, v192
	s_cselect_b32 s0, s0, 0x100
	s_cmp_lg_u32 s36, s35
	s_cselect_b32 s0, s0, 0
	v_lshl_add_u32 v45, v198, 5, s79
	v_add_u32_e32 v199, s70, v44
	ds_read_b128 v[68:71], v45
	ds_read_b128 v[60:63], v45 offset:16
	ds_read_b128 v[72:75], v45 offset:256
	ds_read_b128 v[64:67], v45 offset:272
	ds_read_b128 v[40:43], v45 offset:128
	ds_read_b128 v[32:35], v45 offset:144
	v_add_u32_e32 v44, s0, v199
	v_lshl_add_u32 v48, v44, 3, v197
	ds_read2_b64 v[172:175], v48 offset1:16
	ds_read_b128 v[56:59], v45 offset:384
	ds_read_b128 v[44:47], v45 offset:400
	ds_read2_b64 v[136:139], v48 offset0:32 offset1:48
	ds_read2_b64 v[100:103], v48 offset0:128 offset1:144
	ds_read2_b64 v[48:51], v48 offset0:160 offset1:176
	s_waitcnt lgkmcnt(0)
	s_cmp_gt_i32 s61, 1
	s_mov_b64 s[46:47], -1
	s_mov_b64 s[46:47], 0
	s_andn2_b64 vcc, exec, s[46:47]
	s_add_i32 s0, s74, 0xfffff400
	s_lshl_b64 s[46:47], s[0:1], 1
	s_add_u32 s0, s56, s46
	s_addc_u32 s37, s57, s47
	s_ashr_i32 s75, s74, 31
	s_lshl_b64 s[46:47], s[74:75], 1
	s_add_u32 s46, s42, s46
	s_addc_u32 s47, s43, s47
	s_cmp_lt_i32 s40, 12
	s_cselect_b32 s0, s46, s0
	v_pk_fma_f32 v[204:205], v[68:69], v[172:173], v[72:73] op_sel:[0,1,0]
	v_pk_fma_f32 v[206:207], v[70:71], v[172:173], v[74:75] op_sel:[0,1,0]
	v_pk_fma_f32 v[208:209], v[60:61], v[172:173], v[64:65] op_sel:[0,1,0]
	v_pk_fma_f32 v[210:211], v[62:63], v[172:173], v[66:67] op_sel:[0,1,0]
	v_pk_fma_f32 v[204:205], v[168:169], v[172:173], v[204:205] op_sel_hi:[1,0,1]
	v_pk_fma_f32 v[206:207], v[170:171], v[172:173], v[206:207] op_sel_hi:[1,0,1]
	v_pk_fma_f32 v[208:209], v[164:165], v[172:173], v[208:209] op_sel_hi:[1,0,1]
	v_pk_fma_f32 v[210:211], v[166:167], v[172:173], v[210:211] op_sel_hi:[1,0,1]
	v_pk_mul_f32 v[216:217], v[204:205], v[200:201] op_sel_hi:[1,0]
	v_pk_mul_f32 v[218:219], v[206:207], v[200:201] op_sel_hi:[1,0]
	v_pk_mul_f32 v[220:221], v[208:209], v[200:201] op_sel_hi:[1,0]
	v_pk_mul_f32 v[222:223], v[210:211], v[200:201] op_sel_hi:[1,0]
	v_exp_f32_e32 v216, v216
	v_exp_f32_e32 v217, v217
	v_exp_f32_e32 v218, v218
	v_exp_f32_e32 v219, v219
	v_exp_f32_e32 v220, v220
	v_exp_f32_e32 v221, v221
	v_exp_f32_e32 v222, v222
	v_exp_f32_e32 v223, v223
	v_pk_add_f32 v[216:217], v[216:217], v[200:201] op_sel:[0,1] op_sel_hi:[1,1]
	v_pk_add_f32 v[218:219], v[218:219], v[200:201] op_sel:[0,1] op_sel_hi:[1,1]
	v_pk_add_f32 v[220:221], v[220:221], v[200:201] op_sel:[0,1] op_sel_hi:[1,1]
	v_pk_add_f32 v[222:223], v[222:223], v[200:201] op_sel:[0,1] op_sel_hi:[1,1]
	v_rcp_f32_e32 v216, v216
	v_rcp_f32_e32 v217, v217
	v_rcp_f32_e32 v218, v218
	v_rcp_f32_e32 v219, v219
	v_rcp_f32_e32 v220, v220
	v_rcp_f32_e32 v221, v221
	v_rcp_f32_e32 v222, v222
	v_rcp_f32_e32 v223, v223
	v_cvt_pk_bf16_f32 v224, v216, v217
	v_cvt_pk_bf16_f32 v225, v218, v219
	v_cvt_pk_bf16_f32 v226, v220, v221
	v_cvt_pk_bf16_f32 v227, v222, v223
	v_lshl_add_u32 v164, v198, 3, s71
	s_cselect_b32 s37, s47, s37
	v_mov_b32_e32 v166, s0
	s_movk_i32 s0, 0xc00
	v_mov_b32_e32 v167, s37
	s_cselect_b32 s0, s0, 0x800
	v_ashrrev_i32_e32 v165, 31, v164
	v_lshl_add_u32 v198, s36, 8, v199
	v_lshl_add_u64 v[164:165], v[164:165], 1, v[166:167]
	v_mad_i64_i32 v[166:167], s[36:37], s0, v198, 0
	v_lshl_add_u64 v[166:167], v[166:167], 1, v[164:165]
	s_cmp_gt_i32 s61, 1
	s_mov_b64 s[36:37], -1
	global_store_dwordx4 v[166:167], v[224:227], off nt
	s_mov_b64 s[36:37], 0
	s_andn2_b64 vcc, exec, s[36:37]
	v_pk_fma_f32 v[204:205], v[40:41], v[172:173], v[56:57] op_sel:[0,1,0]
	v_pk_fma_f32 v[206:207], v[42:43], v[172:173], v[58:59] op_sel:[0,1,0]
	v_pk_fma_f32 v[208:209], v[32:33], v[172:173], v[44:45] op_sel:[0,1,0]
	v_pk_fma_f32 v[210:211], v[34:35], v[172:173], v[46:47] op_sel:[0,1,0]
	v_pk_fma_f32 v[204:205], v[160:161], v[172:173], v[204:205] op_sel_hi:[1,0,1]
	v_pk_fma_f32 v[206:207], v[162:163], v[172:173], v[206:207] op_sel_hi:[1,0,1]
	v_pk_fma_f32 v[208:209], v[156:157], v[172:173], v[208:209] op_sel_hi:[1,0,1]
	v_pk_fma_f32 v[210:211], v[158:159], v[172:173], v[210:211] op_sel_hi:[1,0,1]
	v_pk_mul_f32 v[216:217], v[204:205], v[200:201] op_sel_hi:[1,0]
	v_pk_mul_f32 v[218:219], v[206:207], v[200:201] op_sel_hi:[1,0]
	v_pk_mul_f32 v[220:221], v[208:209], v[200:201] op_sel_hi:[1,0]
	v_pk_mul_f32 v[222:223], v[210:211], v[200:201] op_sel_hi:[1,0]
	v_exp_f32_e32 v216, v216
	v_exp_f32_e32 v217, v217
	v_exp_f32_e32 v218, v218
	v_exp_f32_e32 v219, v219
	v_exp_f32_e32 v220, v220
	v_exp_f32_e32 v221, v221
	v_exp_f32_e32 v222, v222
	v_exp_f32_e32 v223, v223
	v_pk_add_f32 v[216:217], v[216:217], v[200:201] op_sel:[0,1] op_sel_hi:[1,1]
	v_pk_add_f32 v[218:219], v[218:219], v[200:201] op_sel:[0,1] op_sel_hi:[1,1]
	v_pk_add_f32 v[220:221], v[220:221], v[200:201] op_sel:[0,1] op_sel_hi:[1,1]
	v_pk_add_f32 v[222:223], v[222:223], v[200:201] op_sel:[0,1] op_sel_hi:[1,1]
	v_rcp_f32_e32 v216, v216
	v_rcp_f32_e32 v217, v217
	v_rcp_f32_e32 v218, v218
	v_rcp_f32_e32 v219, v219
	v_rcp_f32_e32 v220, v220
	v_rcp_f32_e32 v221, v221
	v_rcp_f32_e32 v222, v222
	v_rcp_f32_e32 v223, v223
	v_cvt_pk_bf16_f32 v228, v216, v217
	v_cvt_pk_bf16_f32 v229, v218, v219
	v_cvt_pk_bf16_f32 v230, v220, v221
	v_cvt_pk_bf16_f32 v231, v222, v223
	global_store_dwordx4 v[166:167], v[228:231], off offset:256 nt
	s_cmp_gt_i32 s61, 1
	s_mov_b64 s[36:37], -1
	s_mov_b64 s[36:37], 0
	s_andn2_b64 vcc, exec, s[36:37]
	v_pk_fma_f32 v[204:205], v[68:69], v[174:175], v[72:73] op_sel:[0,1,0]
	v_pk_fma_f32 v[206:207], v[70:71], v[174:175], v[74:75] op_sel:[0,1,0]
	v_pk_fma_f32 v[208:209], v[60:61], v[174:175], v[64:65] op_sel:[0,1,0]
	v_pk_fma_f32 v[210:211], v[62:63], v[174:175], v[66:67] op_sel:[0,1,0]
	v_pk_fma_f32 v[204:205], v[152:153], v[174:175], v[204:205] op_sel_hi:[1,0,1]
	v_pk_fma_f32 v[206:207], v[154:155], v[174:175], v[206:207] op_sel_hi:[1,0,1]
	v_pk_fma_f32 v[208:209], v[148:149], v[174:175], v[208:209] op_sel_hi:[1,0,1]
	v_pk_fma_f32 v[210:211], v[150:151], v[174:175], v[210:211] op_sel_hi:[1,0,1]
	v_pk_mul_f32 v[216:217], v[204:205], v[200:201] op_sel_hi:[1,0]
	v_pk_mul_f32 v[218:219], v[206:207], v[200:201] op_sel_hi:[1,0]
	v_pk_mul_f32 v[220:221], v[208:209], v[200:201] op_sel_hi:[1,0]
	v_pk_mul_f32 v[222:223], v[210:211], v[200:201] op_sel_hi:[1,0]
	v_exp_f32_e32 v216, v216
	v_exp_f32_e32 v217, v217
	v_exp_f32_e32 v218, v218
	v_exp_f32_e32 v219, v219
	v_exp_f32_e32 v220, v220
	v_exp_f32_e32 v221, v221
	v_exp_f32_e32 v222, v222
	v_exp_f32_e32 v223, v223
	v_pk_add_f32 v[216:217], v[216:217], v[200:201] op_sel:[0,1] op_sel_hi:[1,1]
	v_pk_add_f32 v[218:219], v[218:219], v[200:201] op_sel:[0,1] op_sel_hi:[1,1]
	v_pk_add_f32 v[220:221], v[220:221], v[200:201] op_sel:[0,1] op_sel_hi:[1,1]
	v_pk_add_f32 v[222:223], v[222:223], v[200:201] op_sel:[0,1] op_sel_hi:[1,1]
	v_rcp_f32_e32 v216, v216
	v_rcp_f32_e32 v217, v217
	v_rcp_f32_e32 v218, v218
	v_rcp_f32_e32 v219, v219
	v_rcp_f32_e32 v220, v220
	v_rcp_f32_e32 v221, v221
	v_rcp_f32_e32 v222, v222
	v_rcp_f32_e32 v223, v223
	v_cvt_pk_bf16_f32 v232, v216, v217
	v_cvt_pk_bf16_f32 v233, v218, v219
	v_cvt_pk_bf16_f32 v234, v220, v221
	v_cvt_pk_bf16_f32 v235, v222, v223
	v_add_u32_e32 v148, 16, v198
	v_mad_i64_i32 v[148:149], s[36:37], s0, v148, 0
	v_lshl_add_u64 v[148:149], v[148:149], 1, v[164:165]
	global_store_dwordx4 v[148:149], v[232:235], off nt
	s_cmp_gt_i32 s61, 1
	s_mov_b64 s[36:37], -1
	s_mov_b64 s[36:37], 0
	s_andn2_b64 vcc, exec, s[36:37]
	v_pk_fma_f32 v[204:205], v[40:41], v[174:175], v[56:57] op_sel:[0,1,0]
	v_pk_fma_f32 v[206:207], v[42:43], v[174:175], v[58:59] op_sel:[0,1,0]
	v_pk_fma_f32 v[208:209], v[32:33], v[174:175], v[44:45] op_sel:[0,1,0]
	v_pk_fma_f32 v[210:211], v[34:35], v[174:175], v[46:47] op_sel:[0,1,0]
	v_pk_fma_f32 v[204:205], v[144:145], v[174:175], v[204:205] op_sel_hi:[1,0,1]
	v_pk_fma_f32 v[206:207], v[146:147], v[174:175], v[206:207] op_sel_hi:[1,0,1]
	v_pk_fma_f32 v[208:209], v[140:141], v[174:175], v[208:209] op_sel_hi:[1,0,1]
	v_pk_fma_f32 v[210:211], v[142:143], v[174:175], v[210:211] op_sel_hi:[1,0,1]
	v_pk_mul_f32 v[216:217], v[204:205], v[200:201] op_sel_hi:[1,0]
	v_pk_mul_f32 v[218:219], v[206:207], v[200:201] op_sel_hi:[1,0]
	v_pk_mul_f32 v[220:221], v[208:209], v[200:201] op_sel_hi:[1,0]
	v_pk_mul_f32 v[222:223], v[210:211], v[200:201] op_sel_hi:[1,0]
	v_exp_f32_e32 v216, v216
	v_exp_f32_e32 v217, v217
	v_exp_f32_e32 v218, v218
	v_exp_f32_e32 v219, v219
	v_exp_f32_e32 v220, v220
	v_exp_f32_e32 v221, v221
	v_exp_f32_e32 v222, v222
	v_exp_f32_e32 v223, v223
	v_pk_add_f32 v[216:217], v[216:217], v[200:201] op_sel:[0,1] op_sel_hi:[1,1]
	v_pk_add_f32 v[218:219], v[218:219], v[200:201] op_sel:[0,1] op_sel_hi:[1,1]
	v_pk_add_f32 v[220:221], v[220:221], v[200:201] op_sel:[0,1] op_sel_hi:[1,1]
	v_pk_add_f32 v[222:223], v[222:223], v[200:201] op_sel:[0,1] op_sel_hi:[1,1]
	v_rcp_f32_e32 v216, v216
	v_rcp_f32_e32 v217, v217
	v_rcp_f32_e32 v218, v218
	v_rcp_f32_e32 v219, v219
	v_rcp_f32_e32 v220, v220
	v_rcp_f32_e32 v221, v221
	v_rcp_f32_e32 v222, v222
	v_rcp_f32_e32 v223, v223
	v_cvt_pk_bf16_f32 v236, v216, v217
	v_cvt_pk_bf16_f32 v237, v218, v219
	v_cvt_pk_bf16_f32 v238, v220, v221
	v_cvt_pk_bf16_f32 v239, v222, v223
	global_store_dwordx4 v[148:149], v[236:239], off offset:256 nt
	s_cmp_gt_i32 s61, 1
	s_mov_b64 s[36:37], -1
	s_mov_b64 s[36:37], 0
	s_andn2_b64 vcc, exec, s[36:37]
	v_pk_fma_f32 v[204:205], v[68:69], v[136:137], v[72:73] op_sel:[0,1,0]
	v_pk_fma_f32 v[206:207], v[70:71], v[136:137], v[74:75] op_sel:[0,1,0]
	v_pk_fma_f32 v[208:209], v[60:61], v[136:137], v[64:65] op_sel:[0,1,0]
	v_pk_fma_f32 v[210:211], v[62:63], v[136:137], v[66:67] op_sel:[0,1,0]
	v_pk_fma_f32 v[204:205], v[132:133], v[136:137], v[204:205] op_sel_hi:[1,0,1]
	v_pk_fma_f32 v[206:207], v[134:135], v[136:137], v[206:207] op_sel_hi:[1,0,1]
	v_pk_fma_f32 v[208:209], v[128:129], v[136:137], v[208:209] op_sel_hi:[1,0,1]
	v_pk_fma_f32 v[210:211], v[130:131], v[136:137], v[210:211] op_sel_hi:[1,0,1]
	v_pk_mul_f32 v[216:217], v[204:205], v[200:201] op_sel_hi:[1,0]
	v_pk_mul_f32 v[218:219], v[206:207], v[200:201] op_sel_hi:[1,0]
	v_pk_mul_f32 v[220:221], v[208:209], v[200:201] op_sel_hi:[1,0]
	v_pk_mul_f32 v[222:223], v[210:211], v[200:201] op_sel_hi:[1,0]
	v_exp_f32_e32 v216, v216
	v_exp_f32_e32 v217, v217
	v_exp_f32_e32 v218, v218
	v_exp_f32_e32 v219, v219
	v_exp_f32_e32 v220, v220
	v_exp_f32_e32 v221, v221
	v_exp_f32_e32 v222, v222
	v_exp_f32_e32 v223, v223
	v_pk_add_f32 v[216:217], v[216:217], v[200:201] op_sel:[0,1] op_sel_hi:[1,1]
	v_pk_add_f32 v[218:219], v[218:219], v[200:201] op_sel:[0,1] op_sel_hi:[1,1]
	v_pk_add_f32 v[220:221], v[220:221], v[200:201] op_sel:[0,1] op_sel_hi:[1,1]
	v_pk_add_f32 v[222:223], v[222:223], v[200:201] op_sel:[0,1] op_sel_hi:[1,1]
	v_rcp_f32_e32 v216, v216
	v_rcp_f32_e32 v217, v217
	v_rcp_f32_e32 v218, v218
	v_rcp_f32_e32 v219, v219
	v_rcp_f32_e32 v220, v220
	v_rcp_f32_e32 v221, v221
	v_rcp_f32_e32 v222, v222
	v_rcp_f32_e32 v223, v223
	v_cvt_pk_bf16_f32 v240, v216, v217
	v_cvt_pk_bf16_f32 v241, v218, v219
	v_cvt_pk_bf16_f32 v242, v220, v221
	v_cvt_pk_bf16_f32 v243, v222, v223
	v_add_u32_e32 v128, 32, v198
	v_mad_i64_i32 v[128:129], s[36:37], s0, v128, 0
	v_lshl_add_u64 v[128:129], v[128:129], 1, v[164:165]
	s_cmp_gt_i32 s61, 1
	s_mov_b64 s[36:37], -1
	global_store_dwordx4 v[128:129], v[240:243], off nt
	s_mov_b64 s[36:37], 0
	s_andn2_b64 vcc, exec, s[36:37]
	v_pk_fma_f32 v[204:205], v[40:41], v[136:137], v[56:57] op_sel:[0,1,0]
	v_pk_fma_f32 v[206:207], v[42:43], v[136:137], v[58:59] op_sel:[0,1,0]
	v_pk_fma_f32 v[208:209], v[32:33], v[136:137], v[44:45] op_sel:[0,1,0]
	v_pk_fma_f32 v[210:211], v[34:35], v[136:137], v[46:47] op_sel:[0,1,0]
	v_pk_fma_f32 v[204:205], v[124:125], v[136:137], v[204:205] op_sel_hi:[1,0,1]
	v_pk_fma_f32 v[206:207], v[126:127], v[136:137], v[206:207] op_sel_hi:[1,0,1]
	v_pk_fma_f32 v[208:209], v[120:121], v[136:137], v[208:209] op_sel_hi:[1,0,1]
	v_pk_fma_f32 v[210:211], v[122:123], v[136:137], v[210:211] op_sel_hi:[1,0,1]
	v_pk_mul_f32 v[216:217], v[204:205], v[200:201] op_sel_hi:[1,0]
	v_pk_mul_f32 v[218:219], v[206:207], v[200:201] op_sel_hi:[1,0]
	v_pk_mul_f32 v[220:221], v[208:209], v[200:201] op_sel_hi:[1,0]
	v_pk_mul_f32 v[222:223], v[210:211], v[200:201] op_sel_hi:[1,0]
	v_exp_f32_e32 v216, v216
	v_exp_f32_e32 v217, v217
	v_exp_f32_e32 v218, v218
	v_exp_f32_e32 v219, v219
	v_exp_f32_e32 v220, v220
	v_exp_f32_e32 v221, v221
	v_exp_f32_e32 v222, v222
	v_exp_f32_e32 v223, v223
	v_pk_add_f32 v[216:217], v[216:217], v[200:201] op_sel:[0,1] op_sel_hi:[1,1]
	v_pk_add_f32 v[218:219], v[218:219], v[200:201] op_sel:[0,1] op_sel_hi:[1,1]
	v_pk_add_f32 v[220:221], v[220:221], v[200:201] op_sel:[0,1] op_sel_hi:[1,1]
	v_pk_add_f32 v[222:223], v[222:223], v[200:201] op_sel:[0,1] op_sel_hi:[1,1]
	v_rcp_f32_e32 v216, v216
	v_rcp_f32_e32 v217, v217
	v_rcp_f32_e32 v218, v218
	v_rcp_f32_e32 v219, v219
	v_rcp_f32_e32 v220, v220
	v_rcp_f32_e32 v221, v221
	v_rcp_f32_e32 v222, v222
	v_rcp_f32_e32 v223, v223
	v_cvt_pk_bf16_f32 v244, v216, v217
	v_cvt_pk_bf16_f32 v245, v218, v219
	v_cvt_pk_bf16_f32 v246, v220, v221
	v_cvt_pk_bf16_f32 v247, v222, v223
	global_store_dwordx4 v[128:129], v[244:247], off offset:256 nt
	s_cmp_gt_i32 s61, 1
	s_mov_b64 s[36:37], -1
	s_mov_b64 s[36:37], 0
	s_andn2_b64 vcc, exec, s[36:37]
	v_pk_fma_f32 v[204:205], v[68:69], v[138:139], v[72:73] op_sel:[0,1,0]
	v_pk_fma_f32 v[206:207], v[70:71], v[138:139], v[74:75] op_sel:[0,1,0]
	v_pk_fma_f32 v[208:209], v[60:61], v[138:139], v[64:65] op_sel:[0,1,0]
	v_pk_fma_f32 v[210:211], v[62:63], v[138:139], v[66:67] op_sel:[0,1,0]
	v_pk_fma_f32 v[204:205], v[116:117], v[138:139], v[204:205] op_sel_hi:[1,0,1]
	v_pk_fma_f32 v[206:207], v[118:119], v[138:139], v[206:207] op_sel_hi:[1,0,1]
	v_pk_fma_f32 v[208:209], v[112:113], v[138:139], v[208:209] op_sel_hi:[1,0,1]
	v_pk_fma_f32 v[210:211], v[114:115], v[138:139], v[210:211] op_sel_hi:[1,0,1]
	v_pk_mul_f32 v[216:217], v[204:205], v[200:201] op_sel_hi:[1,0]
	v_pk_mul_f32 v[218:219], v[206:207], v[200:201] op_sel_hi:[1,0]
	v_pk_mul_f32 v[220:221], v[208:209], v[200:201] op_sel_hi:[1,0]
	v_pk_mul_f32 v[222:223], v[210:211], v[200:201] op_sel_hi:[1,0]
	v_exp_f32_e32 v216, v216
	v_exp_f32_e32 v217, v217
	v_exp_f32_e32 v218, v218
	v_exp_f32_e32 v219, v219
	v_exp_f32_e32 v220, v220
	v_exp_f32_e32 v221, v221
	v_exp_f32_e32 v222, v222
	v_exp_f32_e32 v223, v223
	v_pk_add_f32 v[216:217], v[216:217], v[200:201] op_sel:[0,1] op_sel_hi:[1,1]
	v_pk_add_f32 v[218:219], v[218:219], v[200:201] op_sel:[0,1] op_sel_hi:[1,1]
	v_pk_add_f32 v[220:221], v[220:221], v[200:201] op_sel:[0,1] op_sel_hi:[1,1]
	v_pk_add_f32 v[222:223], v[222:223], v[200:201] op_sel:[0,1] op_sel_hi:[1,1]
	v_rcp_f32_e32 v216, v216
	v_rcp_f32_e32 v217, v217
	v_rcp_f32_e32 v218, v218
	v_rcp_f32_e32 v219, v219
	v_rcp_f32_e32 v220, v220
	v_rcp_f32_e32 v221, v221
	v_rcp_f32_e32 v222, v222
	v_rcp_f32_e32 v223, v223
	v_cvt_pk_bf16_f32 v248, v216, v217
	v_cvt_pk_bf16_f32 v249, v218, v219
	v_cvt_pk_bf16_f32 v250, v220, v221
	v_cvt_pk_bf16_f32 v251, v222, v223
	v_add_u32_e32 v112, 48, v198
	v_mad_i64_i32 v[112:113], s[36:37], s0, v112, 0
	v_lshl_add_u64 v[112:113], v[112:113], 1, v[164:165]
	global_store_dwordx4 v[112:113], v[248:251], off nt
	s_cmp_gt_i32 s61, 1
	s_mov_b64 s[36:37], -1
	s_mov_b64 s[36:37], 0
	s_andn2_b64 vcc, exec, s[36:37]
	v_pk_fma_f32 v[204:205], v[40:41], v[138:139], v[56:57] op_sel:[0,1,0]
	v_pk_fma_f32 v[206:207], v[42:43], v[138:139], v[58:59] op_sel:[0,1,0]
	v_pk_fma_f32 v[208:209], v[32:33], v[138:139], v[44:45] op_sel:[0,1,0]
	v_pk_fma_f32 v[210:211], v[34:35], v[138:139], v[46:47] op_sel:[0,1,0]
	v_pk_fma_f32 v[204:205], v[108:109], v[138:139], v[204:205] op_sel_hi:[1,0,1]
	v_pk_fma_f32 v[206:207], v[110:111], v[138:139], v[206:207] op_sel_hi:[1,0,1]
	v_pk_fma_f32 v[208:209], v[104:105], v[138:139], v[208:209] op_sel_hi:[1,0,1]
	v_pk_fma_f32 v[210:211], v[106:107], v[138:139], v[210:211] op_sel_hi:[1,0,1]
	v_pk_mul_f32 v[216:217], v[204:205], v[200:201] op_sel_hi:[1,0]
	v_pk_mul_f32 v[218:219], v[206:207], v[200:201] op_sel_hi:[1,0]
	v_pk_mul_f32 v[220:221], v[208:209], v[200:201] op_sel_hi:[1,0]
	v_pk_mul_f32 v[222:223], v[210:211], v[200:201] op_sel_hi:[1,0]
	v_exp_f32_e32 v216, v216
	v_exp_f32_e32 v217, v217
	v_exp_f32_e32 v218, v218
	v_exp_f32_e32 v219, v219
	v_exp_f32_e32 v220, v220
	v_exp_f32_e32 v221, v221
	v_exp_f32_e32 v222, v222
	v_exp_f32_e32 v223, v223
	v_pk_add_f32 v[216:217], v[216:217], v[200:201] op_sel:[0,1] op_sel_hi:[1,1]
	v_pk_add_f32 v[218:219], v[218:219], v[200:201] op_sel:[0,1] op_sel_hi:[1,1]
	v_pk_add_f32 v[220:221], v[220:221], v[200:201] op_sel:[0,1] op_sel_hi:[1,1]
	v_pk_add_f32 v[222:223], v[222:223], v[200:201] op_sel:[0,1] op_sel_hi:[1,1]
	v_rcp_f32_e32 v216, v216
	v_rcp_f32_e32 v217, v217
	v_rcp_f32_e32 v218, v218
	v_rcp_f32_e32 v219, v219
	v_rcp_f32_e32 v220, v220
	v_rcp_f32_e32 v221, v221
	v_rcp_f32_e32 v222, v222
	v_rcp_f32_e32 v223, v223
	v_cvt_pk_bf16_f32 v224, v216, v217
	v_cvt_pk_bf16_f32 v225, v218, v219
	v_cvt_pk_bf16_f32 v226, v220, v221
	v_cvt_pk_bf16_f32 v227, v222, v223
	global_store_dwordx4 v[112:113], v[224:227], off offset:256 nt
	s_cmp_gt_i32 s61, 1
	s_mov_b64 s[36:37], -1
	s_mov_b64 s[36:37], 0
	s_andn2_b64 vcc, exec, s[36:37]
	v_pk_fma_f32 v[204:205], v[68:69], v[100:101], v[72:73] op_sel:[0,1,0]
	v_pk_fma_f32 v[206:207], v[70:71], v[100:101], v[74:75] op_sel:[0,1,0]
	v_pk_fma_f32 v[208:209], v[60:61], v[100:101], v[64:65] op_sel:[0,1,0]
	v_pk_fma_f32 v[210:211], v[62:63], v[100:101], v[66:67] op_sel:[0,1,0]
	v_pk_fma_f32 v[204:205], v[96:97], v[100:101], v[204:205] op_sel_hi:[1,0,1]
	v_pk_fma_f32 v[206:207], v[98:99], v[100:101], v[206:207] op_sel_hi:[1,0,1]
	v_pk_fma_f32 v[208:209], v[92:93], v[100:101], v[208:209] op_sel_hi:[1,0,1]
	v_pk_fma_f32 v[210:211], v[94:95], v[100:101], v[210:211] op_sel_hi:[1,0,1]
	v_pk_mul_f32 v[216:217], v[204:205], v[200:201] op_sel_hi:[1,0]
	v_pk_mul_f32 v[218:219], v[206:207], v[200:201] op_sel_hi:[1,0]
	v_pk_mul_f32 v[220:221], v[208:209], v[200:201] op_sel_hi:[1,0]
	v_pk_mul_f32 v[222:223], v[210:211], v[200:201] op_sel_hi:[1,0]
	v_exp_f32_e32 v216, v216
	v_exp_f32_e32 v217, v217
	v_exp_f32_e32 v218, v218
	v_exp_f32_e32 v219, v219
	v_exp_f32_e32 v220, v220
	v_exp_f32_e32 v221, v221
	v_exp_f32_e32 v222, v222
	v_exp_f32_e32 v223, v223
	v_pk_add_f32 v[216:217], v[216:217], v[200:201] op_sel:[0,1] op_sel_hi:[1,1]
	v_pk_add_f32 v[218:219], v[218:219], v[200:201] op_sel:[0,1] op_sel_hi:[1,1]
	v_pk_add_f32 v[220:221], v[220:221], v[200:201] op_sel:[0,1] op_sel_hi:[1,1]
	v_pk_add_f32 v[222:223], v[222:223], v[200:201] op_sel:[0,1] op_sel_hi:[1,1]
	v_rcp_f32_e32 v216, v216
	v_rcp_f32_e32 v217, v217
	v_rcp_f32_e32 v218, v218
	v_rcp_f32_e32 v219, v219
	v_rcp_f32_e32 v220, v220
	v_rcp_f32_e32 v221, v221
	v_rcp_f32_e32 v222, v222
	v_rcp_f32_e32 v223, v223
	v_cvt_pk_bf16_f32 v228, v216, v217
	v_cvt_pk_bf16_f32 v229, v218, v219
	v_cvt_pk_bf16_f32 v230, v220, v221
	v_cvt_pk_bf16_f32 v231, v222, v223
	v_add_u32_e32 v92, 0x80, v198
	v_mad_i64_i32 v[92:93], s[36:37], s0, v92, 0
	v_lshl_add_u64 v[92:93], v[92:93], 1, v[164:165]
	s_cmp_gt_i32 s61, 1
	s_mov_b64 s[36:37], -1
	global_store_dwordx4 v[92:93], v[228:231], off nt
	s_mov_b64 s[36:37], 0
	s_andn2_b64 vcc, exec, s[36:37]
	v_pk_fma_f32 v[204:205], v[40:41], v[100:101], v[56:57] op_sel:[0,1,0]
	v_pk_fma_f32 v[206:207], v[42:43], v[100:101], v[58:59] op_sel:[0,1,0]
	v_pk_fma_f32 v[208:209], v[32:33], v[100:101], v[44:45] op_sel:[0,1,0]
	v_pk_fma_f32 v[210:211], v[34:35], v[100:101], v[46:47] op_sel:[0,1,0]
	v_pk_fma_f32 v[204:205], v[88:89], v[100:101], v[204:205] op_sel_hi:[1,0,1]
	v_pk_fma_f32 v[206:207], v[90:91], v[100:101], v[206:207] op_sel_hi:[1,0,1]
	v_pk_fma_f32 v[208:209], v[84:85], v[100:101], v[208:209] op_sel_hi:[1,0,1]
	v_pk_fma_f32 v[210:211], v[86:87], v[100:101], v[210:211] op_sel_hi:[1,0,1]
	v_pk_mul_f32 v[216:217], v[204:205], v[200:201] op_sel_hi:[1,0]
	v_pk_mul_f32 v[218:219], v[206:207], v[200:201] op_sel_hi:[1,0]
	v_pk_mul_f32 v[220:221], v[208:209], v[200:201] op_sel_hi:[1,0]
	v_pk_mul_f32 v[222:223], v[210:211], v[200:201] op_sel_hi:[1,0]
	v_exp_f32_e32 v216, v216
	v_exp_f32_e32 v217, v217
	v_exp_f32_e32 v218, v218
	v_exp_f32_e32 v219, v219
	v_exp_f32_e32 v220, v220
	v_exp_f32_e32 v221, v221
	v_exp_f32_e32 v222, v222
	v_exp_f32_e32 v223, v223
	v_pk_add_f32 v[216:217], v[216:217], v[200:201] op_sel:[0,1] op_sel_hi:[1,1]
	v_pk_add_f32 v[218:219], v[218:219], v[200:201] op_sel:[0,1] op_sel_hi:[1,1]
	v_pk_add_f32 v[220:221], v[220:221], v[200:201] op_sel:[0,1] op_sel_hi:[1,1]
	v_pk_add_f32 v[222:223], v[222:223], v[200:201] op_sel:[0,1] op_sel_hi:[1,1]
	v_rcp_f32_e32 v216, v216
	v_rcp_f32_e32 v217, v217
	v_rcp_f32_e32 v218, v218
	v_rcp_f32_e32 v219, v219
	v_rcp_f32_e32 v220, v220
	v_rcp_f32_e32 v221, v221
	v_rcp_f32_e32 v222, v222
	v_rcp_f32_e32 v223, v223
	v_cvt_pk_bf16_f32 v232, v216, v217
	v_cvt_pk_bf16_f32 v233, v218, v219
	v_cvt_pk_bf16_f32 v234, v220, v221
	v_cvt_pk_bf16_f32 v235, v222, v223
	global_store_dwordx4 v[92:93], v[232:235], off offset:256 nt
	s_cmp_gt_i32 s61, 1
	s_mov_b64 s[36:37], -1
	s_mov_b64 s[36:37], 0
	s_andn2_b64 vcc, exec, s[36:37]
	v_pk_fma_f32 v[204:205], v[68:69], v[102:103], v[72:73] op_sel:[0,1,0]
	v_pk_fma_f32 v[206:207], v[70:71], v[102:103], v[74:75] op_sel:[0,1,0]
	v_pk_fma_f32 v[208:209], v[60:61], v[102:103], v[64:65] op_sel:[0,1,0]
	v_pk_fma_f32 v[210:211], v[62:63], v[102:103], v[66:67] op_sel:[0,1,0]
	v_pk_fma_f32 v[204:205], v[80:81], v[102:103], v[204:205] op_sel_hi:[1,0,1]
	v_pk_fma_f32 v[206:207], v[82:83], v[102:103], v[206:207] op_sel_hi:[1,0,1]
	v_pk_fma_f32 v[208:209], v[76:77], v[102:103], v[208:209] op_sel_hi:[1,0,1]
	v_pk_fma_f32 v[210:211], v[78:79], v[102:103], v[210:211] op_sel_hi:[1,0,1]
	v_pk_mul_f32 v[216:217], v[204:205], v[200:201] op_sel_hi:[1,0]
	v_pk_mul_f32 v[218:219], v[206:207], v[200:201] op_sel_hi:[1,0]
	v_pk_mul_f32 v[220:221], v[208:209], v[200:201] op_sel_hi:[1,0]
	v_pk_mul_f32 v[222:223], v[210:211], v[200:201] op_sel_hi:[1,0]
	v_exp_f32_e32 v216, v216
	v_exp_f32_e32 v217, v217
	v_exp_f32_e32 v218, v218
	v_exp_f32_e32 v219, v219
	v_exp_f32_e32 v220, v220
	v_exp_f32_e32 v221, v221
	v_exp_f32_e32 v222, v222
	v_exp_f32_e32 v223, v223
	v_pk_add_f32 v[216:217], v[216:217], v[200:201] op_sel:[0,1] op_sel_hi:[1,1]
	v_pk_add_f32 v[218:219], v[218:219], v[200:201] op_sel:[0,1] op_sel_hi:[1,1]
	v_pk_add_f32 v[220:221], v[220:221], v[200:201] op_sel:[0,1] op_sel_hi:[1,1]
	v_pk_add_f32 v[222:223], v[222:223], v[200:201] op_sel:[0,1] op_sel_hi:[1,1]
	v_rcp_f32_e32 v216, v216
	v_rcp_f32_e32 v217, v217
	v_rcp_f32_e32 v218, v218
	v_rcp_f32_e32 v219, v219
	v_rcp_f32_e32 v220, v220
	v_rcp_f32_e32 v221, v221
	v_rcp_f32_e32 v222, v222
	v_rcp_f32_e32 v223, v223
	v_cvt_pk_bf16_f32 v236, v216, v217
	v_cvt_pk_bf16_f32 v237, v218, v219
	v_cvt_pk_bf16_f32 v238, v220, v221
	v_cvt_pk_bf16_f32 v239, v222, v223
	v_add_u32_e32 v76, 0x90, v198
	v_mad_i64_i32 v[76:77], s[36:37], s0, v76, 0
	v_lshl_add_u64 v[76:77], v[76:77], 1, v[164:165]
	global_store_dwordx4 v[76:77], v[236:239], off nt
	s_cmp_gt_i32 s61, 1
	s_mov_b64 s[36:37], -1
	s_mov_b64 s[36:37], 0
	s_andn2_b64 vcc, exec, s[36:37]
	v_pk_fma_f32 v[204:205], v[40:41], v[102:103], v[56:57] op_sel:[0,1,0]
	v_pk_fma_f32 v[206:207], v[42:43], v[102:103], v[58:59] op_sel:[0,1,0]
	v_pk_fma_f32 v[208:209], v[32:33], v[102:103], v[44:45] op_sel:[0,1,0]
	v_pk_fma_f32 v[210:211], v[34:35], v[102:103], v[46:47] op_sel:[0,1,0]
	v_pk_fma_f32 v[204:205], v[52:53], v[102:103], v[204:205] op_sel_hi:[1,0,1]
	v_pk_fma_f32 v[206:207], v[54:55], v[102:103], v[206:207] op_sel_hi:[1,0,1]
	v_pk_fma_f32 v[208:209], v[36:37], v[102:103], v[208:209] op_sel_hi:[1,0,1]
	v_pk_fma_f32 v[210:211], v[38:39], v[102:103], v[210:211] op_sel_hi:[1,0,1]
	v_pk_mul_f32 v[216:217], v[204:205], v[200:201] op_sel_hi:[1,0]
	v_pk_mul_f32 v[218:219], v[206:207], v[200:201] op_sel_hi:[1,0]
	v_pk_mul_f32 v[220:221], v[208:209], v[200:201] op_sel_hi:[1,0]
	v_pk_mul_f32 v[222:223], v[210:211], v[200:201] op_sel_hi:[1,0]
	v_exp_f32_e32 v216, v216
	v_exp_f32_e32 v217, v217
	v_exp_f32_e32 v218, v218
	v_exp_f32_e32 v219, v219
	v_exp_f32_e32 v220, v220
	v_exp_f32_e32 v221, v221
	v_exp_f32_e32 v222, v222
	v_exp_f32_e32 v223, v223
	v_pk_add_f32 v[216:217], v[216:217], v[200:201] op_sel:[0,1] op_sel_hi:[1,1]
	v_pk_add_f32 v[218:219], v[218:219], v[200:201] op_sel:[0,1] op_sel_hi:[1,1]
	v_pk_add_f32 v[220:221], v[220:221], v[200:201] op_sel:[0,1] op_sel_hi:[1,1]
	v_pk_add_f32 v[222:223], v[222:223], v[200:201] op_sel:[0,1] op_sel_hi:[1,1]
	v_rcp_f32_e32 v216, v216
	v_rcp_f32_e32 v217, v217
	v_rcp_f32_e32 v218, v218
	v_rcp_f32_e32 v219, v219
	v_rcp_f32_e32 v220, v220
	v_rcp_f32_e32 v221, v221
	v_rcp_f32_e32 v222, v222
	v_rcp_f32_e32 v223, v223
	v_cvt_pk_bf16_f32 v240, v216, v217
	v_cvt_pk_bf16_f32 v241, v218, v219
	v_cvt_pk_bf16_f32 v242, v220, v221
	v_cvt_pk_bf16_f32 v243, v222, v223
	global_store_dwordx4 v[76:77], v[240:243], off offset:256 nt
	s_cmp_gt_i32 s61, 1
	s_mov_b64 s[36:37], -1
	s_mov_b64 s[36:37], 0
	s_andn2_b64 vcc, exec, s[36:37]
	v_pk_fma_f32 v[204:205], v[68:69], v[48:49], v[72:73] op_sel:[0,1,0]
	v_pk_fma_f32 v[206:207], v[70:71], v[48:49], v[74:75] op_sel:[0,1,0]
	v_pk_fma_f32 v[208:209], v[60:61], v[48:49], v[64:65] op_sel:[0,1,0]
	v_pk_fma_f32 v[210:211], v[62:63], v[48:49], v[66:67] op_sel:[0,1,0]
	v_pk_fma_f32 v[204:205], v[28:29], v[48:49], v[204:205] op_sel_hi:[1,0,1]
	v_pk_fma_f32 v[206:207], v[30:31], v[48:49], v[206:207] op_sel_hi:[1,0,1]
	v_pk_fma_f32 v[208:209], v[24:25], v[48:49], v[208:209] op_sel_hi:[1,0,1]
	v_pk_fma_f32 v[210:211], v[26:27], v[48:49], v[210:211] op_sel_hi:[1,0,1]
	v_pk_mul_f32 v[216:217], v[204:205], v[200:201] op_sel_hi:[1,0]
	v_pk_mul_f32 v[218:219], v[206:207], v[200:201] op_sel_hi:[1,0]
	v_pk_mul_f32 v[220:221], v[208:209], v[200:201] op_sel_hi:[1,0]
	v_pk_mul_f32 v[222:223], v[210:211], v[200:201] op_sel_hi:[1,0]
	v_exp_f32_e32 v216, v216
	v_exp_f32_e32 v217, v217
	v_exp_f32_e32 v218, v218
	v_exp_f32_e32 v219, v219
	v_exp_f32_e32 v220, v220
	v_exp_f32_e32 v221, v221
	v_exp_f32_e32 v222, v222
	v_exp_f32_e32 v223, v223
	v_pk_add_f32 v[216:217], v[216:217], v[200:201] op_sel:[0,1] op_sel_hi:[1,1]
	v_pk_add_f32 v[218:219], v[218:219], v[200:201] op_sel:[0,1] op_sel_hi:[1,1]
	v_pk_add_f32 v[220:221], v[220:221], v[200:201] op_sel:[0,1] op_sel_hi:[1,1]
	v_pk_add_f32 v[222:223], v[222:223], v[200:201] op_sel:[0,1] op_sel_hi:[1,1]
	v_rcp_f32_e32 v216, v216
	v_rcp_f32_e32 v217, v217
	v_rcp_f32_e32 v218, v218
	v_rcp_f32_e32 v219, v219
	v_rcp_f32_e32 v220, v220
	v_rcp_f32_e32 v221, v221
	v_rcp_f32_e32 v222, v222
	v_rcp_f32_e32 v223, v223
	v_cvt_pk_bf16_f32 v244, v216, v217
	v_cvt_pk_bf16_f32 v245, v218, v219
	v_cvt_pk_bf16_f32 v246, v220, v221
	v_cvt_pk_bf16_f32 v247, v222, v223
	v_add_u32_e32 v24, 0xa0, v198
	v_mad_i64_i32 v[24:25], s[36:37], s0, v24, 0
	v_lshl_add_u64 v[24:25], v[24:25], 1, v[164:165]
	s_cmp_gt_i32 s61, 1
	s_mov_b64 s[36:37], -1
	global_store_dwordx4 v[24:25], v[244:247], off nt
	s_mov_b64 s[36:37], 0
	s_andn2_b64 vcc, exec, s[36:37]
	v_pk_fma_f32 v[204:205], v[40:41], v[48:49], v[56:57] op_sel:[0,1,0]
	v_pk_fma_f32 v[206:207], v[42:43], v[48:49], v[58:59] op_sel:[0,1,0]
	v_pk_fma_f32 v[208:209], v[32:33], v[48:49], v[44:45] op_sel:[0,1,0]
	v_pk_fma_f32 v[210:211], v[34:35], v[48:49], v[46:47] op_sel:[0,1,0]
	v_pk_fma_f32 v[204:205], v[20:21], v[48:49], v[204:205] op_sel_hi:[1,0,1]
	v_pk_fma_f32 v[206:207], v[22:23], v[48:49], v[206:207] op_sel_hi:[1,0,1]
	v_pk_fma_f32 v[208:209], v[16:17], v[48:49], v[208:209] op_sel_hi:[1,0,1]
	v_pk_fma_f32 v[210:211], v[18:19], v[48:49], v[210:211] op_sel_hi:[1,0,1]
	v_pk_mul_f32 v[216:217], v[204:205], v[200:201] op_sel_hi:[1,0]
	v_pk_mul_f32 v[218:219], v[206:207], v[200:201] op_sel_hi:[1,0]
	v_pk_mul_f32 v[220:221], v[208:209], v[200:201] op_sel_hi:[1,0]
	v_pk_mul_f32 v[222:223], v[210:211], v[200:201] op_sel_hi:[1,0]
	v_exp_f32_e32 v216, v216
	v_exp_f32_e32 v217, v217
	v_exp_f32_e32 v218, v218
	v_exp_f32_e32 v219, v219
	v_exp_f32_e32 v220, v220
	v_exp_f32_e32 v221, v221
	v_exp_f32_e32 v222, v222
	v_exp_f32_e32 v223, v223
	v_pk_add_f32 v[216:217], v[216:217], v[200:201] op_sel:[0,1] op_sel_hi:[1,1]
	v_pk_add_f32 v[218:219], v[218:219], v[200:201] op_sel:[0,1] op_sel_hi:[1,1]
	v_pk_add_f32 v[220:221], v[220:221], v[200:201] op_sel:[0,1] op_sel_hi:[1,1]
	v_pk_add_f32 v[222:223], v[222:223], v[200:201] op_sel:[0,1] op_sel_hi:[1,1]
	v_rcp_f32_e32 v216, v216
	v_rcp_f32_e32 v217, v217
	v_rcp_f32_e32 v218, v218
	v_rcp_f32_e32 v219, v219
	v_rcp_f32_e32 v220, v220
	v_rcp_f32_e32 v221, v221
	v_rcp_f32_e32 v222, v222
	v_rcp_f32_e32 v223, v223
	v_cvt_pk_bf16_f32 v248, v216, v217
	v_cvt_pk_bf16_f32 v249, v218, v219
	v_cvt_pk_bf16_f32 v250, v220, v221
	v_cvt_pk_bf16_f32 v251, v222, v223
	global_store_dwordx4 v[24:25], v[248:251], off offset:256 nt
	s_cmp_gt_i32 s61, 1
	s_mov_b64 s[36:37], -1
	s_mov_b64 s[36:37], 0
	s_andn2_b64 vcc, exec, s[36:37]
	v_pk_fma_f32 v[204:205], v[68:69], v[50:51], v[72:73] op_sel:[0,1,0]
	v_pk_fma_f32 v[206:207], v[70:71], v[50:51], v[74:75] op_sel:[0,1,0]
	v_pk_fma_f32 v[208:209], v[60:61], v[50:51], v[64:65] op_sel:[0,1,0]
	v_pk_fma_f32 v[210:211], v[62:63], v[50:51], v[66:67] op_sel:[0,1,0]
	v_pk_fma_f32 v[204:205], v[12:13], v[50:51], v[204:205] op_sel_hi:[1,0,1]
	v_pk_fma_f32 v[206:207], v[14:15], v[50:51], v[206:207] op_sel_hi:[1,0,1]
	v_pk_fma_f32 v[208:209], v[8:9], v[50:51], v[208:209] op_sel_hi:[1,0,1]
	v_pk_fma_f32 v[210:211], v[10:11], v[50:51], v[210:211] op_sel_hi:[1,0,1]
	v_pk_mul_f32 v[216:217], v[204:205], v[200:201] op_sel_hi:[1,0]
	v_pk_mul_f32 v[218:219], v[206:207], v[200:201] op_sel_hi:[1,0]
	v_pk_mul_f32 v[220:221], v[208:209], v[200:201] op_sel_hi:[1,0]
	v_pk_mul_f32 v[222:223], v[210:211], v[200:201] op_sel_hi:[1,0]
	v_exp_f32_e32 v216, v216
	v_exp_f32_e32 v217, v217
	v_exp_f32_e32 v218, v218
	v_exp_f32_e32 v219, v219
	v_exp_f32_e32 v220, v220
	v_exp_f32_e32 v221, v221
	v_exp_f32_e32 v222, v222
	v_exp_f32_e32 v223, v223
	v_pk_add_f32 v[216:217], v[216:217], v[200:201] op_sel:[0,1] op_sel_hi:[1,1]
	v_pk_add_f32 v[218:219], v[218:219], v[200:201] op_sel:[0,1] op_sel_hi:[1,1]
	v_pk_add_f32 v[220:221], v[220:221], v[200:201] op_sel:[0,1] op_sel_hi:[1,1]
	v_pk_add_f32 v[222:223], v[222:223], v[200:201] op_sel:[0,1] op_sel_hi:[1,1]
	v_rcp_f32_e32 v216, v216
	v_rcp_f32_e32 v217, v217
	v_rcp_f32_e32 v218, v218
	v_rcp_f32_e32 v219, v219
	v_rcp_f32_e32 v220, v220
	v_rcp_f32_e32 v221, v221
	v_rcp_f32_e32 v222, v222
	v_rcp_f32_e32 v223, v223
	v_cvt_pk_bf16_f32 v224, v216, v217
	v_cvt_pk_bf16_f32 v225, v218, v219
	v_cvt_pk_bf16_f32 v226, v220, v221
	v_cvt_pk_bf16_f32 v227, v222, v223
	v_add_u32_e32 v8, 0xb0, v198
	v_mad_i64_i32 v[8:9], s[36:37], s0, v8, 0
	v_lshl_add_u64 v[8:9], v[8:9], 1, v[164:165]
	global_store_dwordx4 v[8:9], v[224:227], off nt
	s_cmp_gt_i32 s61, 1
	s_mov_b64 s[36:37], -1
	s_mov_b64 s[36:37], 0
	s_andn2_b64 vcc, exec, s[36:37]
	s_andn2_b64 vcc, exec, s[8:9]
	s_mov_b64 s[8:9], -1
	v_pk_fma_f32 v[204:205], v[40:41], v[50:51], v[56:57] op_sel:[0,1,0]
	v_pk_fma_f32 v[206:207], v[42:43], v[50:51], v[58:59] op_sel:[0,1,0]
	v_pk_fma_f32 v[208:209], v[32:33], v[50:51], v[44:45] op_sel:[0,1,0]
	v_pk_fma_f32 v[210:211], v[34:35], v[50:51], v[46:47] op_sel:[0,1,0]
	v_pk_fma_f32 v[204:205], v[4:5], v[50:51], v[204:205] op_sel_hi:[1,0,1]
	v_pk_fma_f32 v[206:207], v[6:7], v[50:51], v[206:207] op_sel_hi:[1,0,1]
	v_pk_fma_f32 v[208:209], v[0:1], v[50:51], v[208:209] op_sel_hi:[1,0,1]
	v_pk_fma_f32 v[210:211], v[2:3], v[50:51], v[210:211] op_sel_hi:[1,0,1]
	v_pk_mul_f32 v[216:217], v[204:205], v[200:201] op_sel_hi:[1,0]
	v_pk_mul_f32 v[218:219], v[206:207], v[200:201] op_sel_hi:[1,0]
	v_pk_mul_f32 v[220:221], v[208:209], v[200:201] op_sel_hi:[1,0]
	v_pk_mul_f32 v[222:223], v[210:211], v[200:201] op_sel_hi:[1,0]
	v_exp_f32_e32 v216, v216
	v_exp_f32_e32 v217, v217
	v_exp_f32_e32 v218, v218
	v_exp_f32_e32 v219, v219
	v_exp_f32_e32 v220, v220
	v_exp_f32_e32 v221, v221
	v_exp_f32_e32 v222, v222
	v_exp_f32_e32 v223, v223
	v_pk_add_f32 v[216:217], v[216:217], v[200:201] op_sel:[0,1] op_sel_hi:[1,1]
	v_pk_add_f32 v[218:219], v[218:219], v[200:201] op_sel:[0,1] op_sel_hi:[1,1]
	v_pk_add_f32 v[220:221], v[220:221], v[200:201] op_sel:[0,1] op_sel_hi:[1,1]
	v_pk_add_f32 v[222:223], v[222:223], v[200:201] op_sel:[0,1] op_sel_hi:[1,1]
	v_rcp_f32_e32 v216, v216
	v_rcp_f32_e32 v217, v217
	v_rcp_f32_e32 v218, v218
	v_rcp_f32_e32 v219, v219
	v_rcp_f32_e32 v220, v220
	v_rcp_f32_e32 v221, v221
	v_rcp_f32_e32 v222, v222
	v_rcp_f32_e32 v223, v223
	v_cvt_pk_bf16_f32 v228, v216, v217
	v_cvt_pk_bf16_f32 v229, v218, v219
	v_cvt_pk_bf16_f32 v230, v220, v221
	v_cvt_pk_bf16_f32 v231, v222, v223
	global_store_dwordx4 v[8:9], v[228:231], off offset:256 nt

.Le1m2_18:
	v_mov_b32_e32 v200, 0xbfb8aa3b
	v_mov_b32_e32 v201, 1.0
	s_cmp_eq_u32 s36, s69
	s_movk_i32 s0, 0x200
	s_cselect_b32 s0, s0, 0x300
	s_cmp_lg_u32 s36, s68
	v_mov_b32_e32 v44, v192
	v_mov_b32_e32 v198, v193
	s_cselect_b32 s0, s0, 0x100
	s_cmp_lg_u32 s36, s35
	s_cselect_b32 s0, s0, 0
	v_lshl_add_u32 v45, v198, 5, s79
	v_add_u32_e32 v199, s70, v44
	ds_read_b128 v[68:71], v45
	ds_read_b128 v[60:63], v45 offset:16
	ds_read_b128 v[72:75], v45 offset:256
	ds_read_b128 v[64:67], v45 offset:272
	ds_read_b128 v[40:43], v45 offset:128
	ds_read_b128 v[32:35], v45 offset:144
	v_add_u32_e32 v44, s0, v199
	v_lshl_add_u32 v48, v44, 3, v197
	ds_read2_b64 v[172:175], v48 offset1:16
	ds_read_b128 v[56:59], v45 offset:384
	ds_read_b128 v[44:47], v45 offset:400
	ds_read2_b64 v[136:139], v48 offset0:32 offset1:48
	ds_read2_b64 v[100:103], v48 offset0:128 offset1:144
	ds_read2_b64 v[48:51], v48 offset0:160 offset1:176
	s_waitcnt lgkmcnt(0)
	s_cmp_gt_i32 s61, 1
	s_mov_b64 s[46:47], -1
	s_mov_b64 s[46:47], 0
	s_andn2_b64 vcc, exec, s[46:47]
	s_add_i32 s0, s74, 0xfffff400
	s_lshl_b64 s[46:47], s[0:1], 1
	s_add_u32 s0, s56, s46
	s_addc_u32 s37, s57, s47
	s_ashr_i32 s75, s74, 31
	s_lshl_b64 s[46:47], s[74:75], 1
	s_add_u32 s46, s42, s46
	s_addc_u32 s47, s43, s47
	s_cmp_lt_i32 s40, 12
	s_cselect_b32 s0, s46, s0
	v_pk_fma_f32 v[204:205], v[68:69], v[172:173], v[72:73] op_sel:[0,1,0]
	v_pk_fma_f32 v[206:207], v[70:71], v[172:173], v[74:75] op_sel:[0,1,0]
	v_pk_fma_f32 v[208:209], v[60:61], v[172:173], v[64:65] op_sel:[0,1,0]
	v_pk_fma_f32 v[210:211], v[62:63], v[172:173], v[66:67] op_sel:[0,1,0]
	v_pk_fma_f32 v[204:205], v[168:169], v[172:173], v[204:205] op_sel_hi:[1,0,1]
	v_pk_fma_f32 v[206:207], v[170:171], v[172:173], v[206:207] op_sel_hi:[1,0,1]
	v_pk_fma_f32 v[208:209], v[164:165], v[172:173], v[208:209] op_sel_hi:[1,0,1]
	v_pk_fma_f32 v[210:211], v[166:167], v[172:173], v[210:211] op_sel_hi:[1,0,1]
	v_pk_mul_f32 v[216:217], v[204:205], v[200:201] op_sel_hi:[1,0]
	v_pk_mul_f32 v[218:219], v[206:207], v[200:201] op_sel_hi:[1,0]
	v_pk_mul_f32 v[220:221], v[208:209], v[200:201] op_sel_hi:[1,0]
	v_pk_mul_f32 v[222:223], v[210:211], v[200:201] op_sel_hi:[1,0]
	v_exp_f32_e32 v216, v216
	v_exp_f32_e32 v217, v217
	v_exp_f32_e32 v218, v218
	v_exp_f32_e32 v219, v219
	v_exp_f32_e32 v220, v220
	v_exp_f32_e32 v221, v221
	v_exp_f32_e32 v222, v222
	v_exp_f32_e32 v223, v223
	v_pk_add_f32 v[216:217], v[216:217], v[200:201] op_sel:[0,1] op_sel_hi:[1,1]
	v_pk_add_f32 v[218:219], v[218:219], v[200:201] op_sel:[0,1] op_sel_hi:[1,1]
	v_pk_add_f32 v[220:221], v[220:221], v[200:201] op_sel:[0,1] op_sel_hi:[1,1]
	v_pk_add_f32 v[222:223], v[222:223], v[200:201] op_sel:[0,1] op_sel_hi:[1,1]
	v_rcp_f32_e32 v216, v216
	v_rcp_f32_e32 v217, v217
	v_rcp_f32_e32 v218, v218
	v_rcp_f32_e32 v219, v219
	v_rcp_f32_e32 v220, v220
	v_rcp_f32_e32 v221, v221
	v_rcp_f32_e32 v222, v222
	v_rcp_f32_e32 v223, v223
	v_cvt_pk_bf16_f32 v224, v216, v217
	v_cvt_pk_bf16_f32 v225, v218, v219
	v_cvt_pk_bf16_f32 v226, v220, v221
	v_cvt_pk_bf16_f32 v227, v222, v223
	v_lshl_add_u32 v164, v198, 3, s71
	s_cselect_b32 s37, s47, s37
	v_mov_b32_e32 v166, s0
	s_movk_i32 s0, 0xc00
	v_mov_b32_e32 v167, s37
	s_cselect_b32 s0, s0, 0x800
	v_ashrrev_i32_e32 v165, 31, v164
	v_lshl_add_u32 v198, s36, 8, v199
	v_lshl_add_u64 v[164:165], v[164:165], 1, v[166:167]
	v_mad_i64_i32 v[166:167], s[36:37], s0, v198, 0
	v_lshl_add_u64 v[166:167], v[166:167], 1, v[164:165]
	s_cmp_gt_i32 s61, 1
	s_mov_b64 s[36:37], -1
	global_store_dwordx4 v[166:167], v[224:227], off nt
	s_mov_b64 s[36:37], 0
	s_andn2_b64 vcc, exec, s[36:37]
	v_pk_fma_f32 v[204:205], v[40:41], v[172:173], v[56:57] op_sel:[0,1,0]
	v_pk_fma_f32 v[206:207], v[42:43], v[172:173], v[58:59] op_sel:[0,1,0]
	v_pk_fma_f32 v[208:209], v[32:33], v[172:173], v[44:45] op_sel:[0,1,0]
	v_pk_fma_f32 v[210:211], v[34:35], v[172:173], v[46:47] op_sel:[0,1,0]
	v_pk_fma_f32 v[204:205], v[160:161], v[172:173], v[204:205] op_sel_hi:[1,0,1]
	v_pk_fma_f32 v[206:207], v[162:163], v[172:173], v[206:207] op_sel_hi:[1,0,1]
	v_pk_fma_f32 v[208:209], v[156:157], v[172:173], v[208:209] op_sel_hi:[1,0,1]
	v_pk_fma_f32 v[210:211], v[158:159], v[172:173], v[210:211] op_sel_hi:[1,0,1]
	v_pk_mul_f32 v[216:217], v[204:205], v[200:201] op_sel_hi:[1,0]
	v_pk_mul_f32 v[218:219], v[206:207], v[200:201] op_sel_hi:[1,0]
	v_pk_mul_f32 v[220:221], v[208:209], v[200:201] op_sel_hi:[1,0]
	v_pk_mul_f32 v[222:223], v[210:211], v[200:201] op_sel_hi:[1,0]
	v_exp_f32_e32 v216, v216
	v_exp_f32_e32 v217, v217
	v_exp_f32_e32 v218, v218
	v_exp_f32_e32 v219, v219
	v_exp_f32_e32 v220, v220
	v_exp_f32_e32 v221, v221
	v_exp_f32_e32 v222, v222
	v_exp_f32_e32 v223, v223
	v_pk_add_f32 v[216:217], v[216:217], v[200:201] op_sel:[0,1] op_sel_hi:[1,1]
	v_pk_add_f32 v[218:219], v[218:219], v[200:201] op_sel:[0,1] op_sel_hi:[1,1]
	v_pk_add_f32 v[220:221], v[220:221], v[200:201] op_sel:[0,1] op_sel_hi:[1,1]
	v_pk_add_f32 v[222:223], v[222:223], v[200:201] op_sel:[0,1] op_sel_hi:[1,1]
	v_rcp_f32_e32 v216, v216
	v_rcp_f32_e32 v217, v217
	v_rcp_f32_e32 v218, v218
	v_rcp_f32_e32 v219, v219
	v_rcp_f32_e32 v220, v220
	v_rcp_f32_e32 v221, v221
	v_rcp_f32_e32 v222, v222
	v_rcp_f32_e32 v223, v223
	v_cvt_pk_bf16_f32 v228, v216, v217
	v_cvt_pk_bf16_f32 v229, v218, v219
	v_cvt_pk_bf16_f32 v230, v220, v221
	v_cvt_pk_bf16_f32 v231, v222, v223
	global_store_dwordx4 v[166:167], v[228:231], off offset:256 nt
	s_cmp_gt_i32 s61, 1
	s_mov_b64 s[36:37], -1
	s_mov_b64 s[36:37], 0
	s_andn2_b64 vcc, exec, s[36:37]
	v_pk_fma_f32 v[204:205], v[68:69], v[174:175], v[72:73] op_sel:[0,1,0]
	v_pk_fma_f32 v[206:207], v[70:71], v[174:175], v[74:75] op_sel:[0,1,0]
	v_pk_fma_f32 v[208:209], v[60:61], v[174:175], v[64:65] op_sel:[0,1,0]
	v_pk_fma_f32 v[210:211], v[62:63], v[174:175], v[66:67] op_sel:[0,1,0]
	v_pk_fma_f32 v[204:205], v[152:153], v[174:175], v[204:205] op_sel_hi:[1,0,1]
	v_pk_fma_f32 v[206:207], v[154:155], v[174:175], v[206:207] op_sel_hi:[1,0,1]
	v_pk_fma_f32 v[208:209], v[148:149], v[174:175], v[208:209] op_sel_hi:[1,0,1]
	v_pk_fma_f32 v[210:211], v[150:151], v[174:175], v[210:211] op_sel_hi:[1,0,1]
	v_pk_mul_f32 v[216:217], v[204:205], v[200:201] op_sel_hi:[1,0]
	v_pk_mul_f32 v[218:219], v[206:207], v[200:201] op_sel_hi:[1,0]
	v_pk_mul_f32 v[220:221], v[208:209], v[200:201] op_sel_hi:[1,0]
	v_pk_mul_f32 v[222:223], v[210:211], v[200:201] op_sel_hi:[1,0]
	v_exp_f32_e32 v216, v216
	v_exp_f32_e32 v217, v217
	v_exp_f32_e32 v218, v218
	v_exp_f32_e32 v219, v219
	v_exp_f32_e32 v220, v220
	v_exp_f32_e32 v221, v221
	v_exp_f32_e32 v222, v222
	v_exp_f32_e32 v223, v223
	v_pk_add_f32 v[216:217], v[216:217], v[200:201] op_sel:[0,1] op_sel_hi:[1,1]
	v_pk_add_f32 v[218:219], v[218:219], v[200:201] op_sel:[0,1] op_sel_hi:[1,1]
	v_pk_add_f32 v[220:221], v[220:221], v[200:201] op_sel:[0,1] op_sel_hi:[1,1]
	v_pk_add_f32 v[222:223], v[222:223], v[200:201] op_sel:[0,1] op_sel_hi:[1,1]
	v_rcp_f32_e32 v216, v216
	v_rcp_f32_e32 v217, v217
	v_rcp_f32_e32 v218, v218
	v_rcp_f32_e32 v219, v219
	v_rcp_f32_e32 v220, v220
	v_rcp_f32_e32 v221, v221
	v_rcp_f32_e32 v222, v222
	v_rcp_f32_e32 v223, v223
	v_cvt_pk_bf16_f32 v232, v216, v217
	v_cvt_pk_bf16_f32 v233, v218, v219
	v_cvt_pk_bf16_f32 v234, v220, v221
	v_cvt_pk_bf16_f32 v235, v222, v223
	v_add_u32_e32 v148, 16, v198
	v_mad_i64_i32 v[148:149], s[36:37], s0, v148, 0
	v_lshl_add_u64 v[148:149], v[148:149], 1, v[164:165]
	global_store_dwordx4 v[148:149], v[232:235], off nt
	s_cmp_gt_i32 s61, 1
	s_mov_b64 s[36:37], -1
	s_mov_b64 s[36:37], 0
	s_andn2_b64 vcc, exec, s[36:37]
	v_pk_fma_f32 v[204:205], v[40:41], v[174:175], v[56:57] op_sel:[0,1,0]
	v_pk_fma_f32 v[206:207], v[42:43], v[174:175], v[58:59] op_sel:[0,1,0]
	v_pk_fma_f32 v[208:209], v[32:33], v[174:175], v[44:45] op_sel:[0,1,0]
	v_pk_fma_f32 v[210:211], v[34:35], v[174:175], v[46:47] op_sel:[0,1,0]
	v_pk_fma_f32 v[204:205], v[144:145], v[174:175], v[204:205] op_sel_hi:[1,0,1]
	v_pk_fma_f32 v[206:207], v[146:147], v[174:175], v[206:207] op_sel_hi:[1,0,1]
	v_pk_fma_f32 v[208:209], v[140:141], v[174:175], v[208:209] op_sel_hi:[1,0,1]
	v_pk_fma_f32 v[210:211], v[142:143], v[174:175], v[210:211] op_sel_hi:[1,0,1]
	v_pk_mul_f32 v[216:217], v[204:205], v[200:201] op_sel_hi:[1,0]
	v_pk_mul_f32 v[218:219], v[206:207], v[200:201] op_sel_hi:[1,0]
	v_pk_mul_f32 v[220:221], v[208:209], v[200:201] op_sel_hi:[1,0]
	v_pk_mul_f32 v[222:223], v[210:211], v[200:201] op_sel_hi:[1,0]
	v_exp_f32_e32 v216, v216
	v_exp_f32_e32 v217, v217
	v_exp_f32_e32 v218, v218
	v_exp_f32_e32 v219, v219
	v_exp_f32_e32 v220, v220
	v_exp_f32_e32 v221, v221
	v_exp_f32_e32 v222, v222
	v_exp_f32_e32 v223, v223
	v_pk_add_f32 v[216:217], v[216:217], v[200:201] op_sel:[0,1] op_sel_hi:[1,1]
	v_pk_add_f32 v[218:219], v[218:219], v[200:201] op_sel:[0,1] op_sel_hi:[1,1]
	v_pk_add_f32 v[220:221], v[220:221], v[200:201] op_sel:[0,1] op_sel_hi:[1,1]
	v_pk_add_f32 v[222:223], v[222:223], v[200:201] op_sel:[0,1] op_sel_hi:[1,1]
	v_rcp_f32_e32 v216, v216
	v_rcp_f32_e32 v217, v217
	v_rcp_f32_e32 v218, v218
	v_rcp_f32_e32 v219, v219
	v_rcp_f32_e32 v220, v220
	v_rcp_f32_e32 v221, v221
	v_rcp_f32_e32 v222, v222
	v_rcp_f32_e32 v223, v223
	v_cvt_pk_bf16_f32 v236, v216, v217
	v_cvt_pk_bf16_f32 v237, v218, v219
	v_cvt_pk_bf16_f32 v238, v220, v221
	v_cvt_pk_bf16_f32 v239, v222, v223
	global_store_dwordx4 v[148:149], v[236:239], off offset:256 nt
	s_cmp_gt_i32 s61, 1
	s_mov_b64 s[36:37], -1
	s_mov_b64 s[36:37], 0
	s_andn2_b64 vcc, exec, s[36:37]
	v_pk_fma_f32 v[204:205], v[68:69], v[136:137], v[72:73] op_sel:[0,1,0]
	v_pk_fma_f32 v[206:207], v[70:71], v[136:137], v[74:75] op_sel:[0,1,0]
	v_pk_fma_f32 v[208:209], v[60:61], v[136:137], v[64:65] op_sel:[0,1,0]
	v_pk_fma_f32 v[210:211], v[62:63], v[136:137], v[66:67] op_sel:[0,1,0]
	v_pk_fma_f32 v[204:205], v[132:133], v[136:137], v[204:205] op_sel_hi:[1,0,1]
	v_pk_fma_f32 v[206:207], v[134:135], v[136:137], v[206:207] op_sel_hi:[1,0,1]
	v_pk_fma_f32 v[208:209], v[128:129], v[136:137], v[208:209] op_sel_hi:[1,0,1]
	v_pk_fma_f32 v[210:211], v[130:131], v[136:137], v[210:211] op_sel_hi:[1,0,1]
	v_pk_mul_f32 v[216:217], v[204:205], v[200:201] op_sel_hi:[1,0]
	v_pk_mul_f32 v[218:219], v[206:207], v[200:201] op_sel_hi:[1,0]
	v_pk_mul_f32 v[220:221], v[208:209], v[200:201] op_sel_hi:[1,0]
	v_pk_mul_f32 v[222:223], v[210:211], v[200:201] op_sel_hi:[1,0]
	v_exp_f32_e32 v216, v216
	v_exp_f32_e32 v217, v217
	v_exp_f32_e32 v218, v218
	v_exp_f32_e32 v219, v219
	v_exp_f32_e32 v220, v220
	v_exp_f32_e32 v221, v221
	v_exp_f32_e32 v222, v222
	v_exp_f32_e32 v223, v223
	v_pk_add_f32 v[216:217], v[216:217], v[200:201] op_sel:[0,1] op_sel_hi:[1,1]
	v_pk_add_f32 v[218:219], v[218:219], v[200:201] op_sel:[0,1] op_sel_hi:[1,1]
	v_pk_add_f32 v[220:221], v[220:221], v[200:201] op_sel:[0,1] op_sel_hi:[1,1]
	v_pk_add_f32 v[222:223], v[222:223], v[200:201] op_sel:[0,1] op_sel_hi:[1,1]
	v_rcp_f32_e32 v216, v216
	v_rcp_f32_e32 v217, v217
	v_rcp_f32_e32 v218, v218
	v_rcp_f32_e32 v219, v219
	v_rcp_f32_e32 v220, v220
	v_rcp_f32_e32 v221, v221
	v_rcp_f32_e32 v222, v222
	v_rcp_f32_e32 v223, v223
	v_cvt_pk_bf16_f32 v240, v216, v217
	v_cvt_pk_bf16_f32 v241, v218, v219
	v_cvt_pk_bf16_f32 v242, v220, v221
	v_cvt_pk_bf16_f32 v243, v222, v223
	v_add_u32_e32 v128, 32, v198
	v_mad_i64_i32 v[128:129], s[36:37], s0, v128, 0
	v_lshl_add_u64 v[128:129], v[128:129], 1, v[164:165]
	s_cmp_gt_i32 s61, 1
	s_mov_b64 s[36:37], -1
	global_store_dwordx4 v[128:129], v[240:243], off nt
	s_mov_b64 s[36:37], 0
	s_andn2_b64 vcc, exec, s[36:37]
	v_pk_fma_f32 v[204:205], v[40:41], v[136:137], v[56:57] op_sel:[0,1,0]
	v_pk_fma_f32 v[206:207], v[42:43], v[136:137], v[58:59] op_sel:[0,1,0]
	v_pk_fma_f32 v[208:209], v[32:33], v[136:137], v[44:45] op_sel:[0,1,0]
	v_pk_fma_f32 v[210:211], v[34:35], v[136:137], v[46:47] op_sel:[0,1,0]
	v_pk_fma_f32 v[204:205], v[124:125], v[136:137], v[204:205] op_sel_hi:[1,0,1]
	v_pk_fma_f32 v[206:207], v[126:127], v[136:137], v[206:207] op_sel_hi:[1,0,1]
	v_pk_fma_f32 v[208:209], v[120:121], v[136:137], v[208:209] op_sel_hi:[1,0,1]
	v_pk_fma_f32 v[210:211], v[122:123], v[136:137], v[210:211] op_sel_hi:[1,0,1]
	v_pk_mul_f32 v[216:217], v[204:205], v[200:201] op_sel_hi:[1,0]
	v_pk_mul_f32 v[218:219], v[206:207], v[200:201] op_sel_hi:[1,0]
	v_pk_mul_f32 v[220:221], v[208:209], v[200:201] op_sel_hi:[1,0]
	v_pk_mul_f32 v[222:223], v[210:211], v[200:201] op_sel_hi:[1,0]
	v_exp_f32_e32 v216, v216
	v_exp_f32_e32 v217, v217
	v_exp_f32_e32 v218, v218
	v_exp_f32_e32 v219, v219
	v_exp_f32_e32 v220, v220
	v_exp_f32_e32 v221, v221
	v_exp_f32_e32 v222, v222
	v_exp_f32_e32 v223, v223
	v_pk_add_f32 v[216:217], v[216:217], v[200:201] op_sel:[0,1] op_sel_hi:[1,1]
	v_pk_add_f32 v[218:219], v[218:219], v[200:201] op_sel:[0,1] op_sel_hi:[1,1]
	v_pk_add_f32 v[220:221], v[220:221], v[200:201] op_sel:[0,1] op_sel_hi:[1,1]
	v_pk_add_f32 v[222:223], v[222:223], v[200:201] op_sel:[0,1] op_sel_hi:[1,1]
	v_rcp_f32_e32 v216, v216
	v_rcp_f32_e32 v217, v217
	v_rcp_f32_e32 v218, v218
	v_rcp_f32_e32 v219, v219
	v_rcp_f32_e32 v220, v220
	v_rcp_f32_e32 v221, v221
	v_rcp_f32_e32 v222, v222
	v_rcp_f32_e32 v223, v223
	v_cvt_pk_bf16_f32 v244, v216, v217
	v_cvt_pk_bf16_f32 v245, v218, v219
	v_cvt_pk_bf16_f32 v246, v220, v221
	v_cvt_pk_bf16_f32 v247, v222, v223
	global_store_dwordx4 v[128:129], v[244:247], off offset:256 nt
	s_cmp_gt_i32 s61, 1
	s_mov_b64 s[36:37], -1
	s_mov_b64 s[36:37], 0
	s_andn2_b64 vcc, exec, s[36:37]
	v_pk_fma_f32 v[204:205], v[68:69], v[138:139], v[72:73] op_sel:[0,1,0]
	v_pk_fma_f32 v[206:207], v[70:71], v[138:139], v[74:75] op_sel:[0,1,0]
	v_pk_fma_f32 v[208:209], v[60:61], v[138:139], v[64:65] op_sel:[0,1,0]
	v_pk_fma_f32 v[210:211], v[62:63], v[138:139], v[66:67] op_sel:[0,1,0]
	v_pk_fma_f32 v[204:205], v[116:117], v[138:139], v[204:205] op_sel_hi:[1,0,1]
	v_pk_fma_f32 v[206:207], v[118:119], v[138:139], v[206:207] op_sel_hi:[1,0,1]
	v_pk_fma_f32 v[208:209], v[112:113], v[138:139], v[208:209] op_sel_hi:[1,0,1]
	v_pk_fma_f32 v[210:211], v[114:115], v[138:139], v[210:211] op_sel_hi:[1,0,1]
	v_pk_mul_f32 v[216:217], v[204:205], v[200:201] op_sel_hi:[1,0]
	v_pk_mul_f32 v[218:219], v[206:207], v[200:201] op_sel_hi:[1,0]
	v_pk_mul_f32 v[220:221], v[208:209], v[200:201] op_sel_hi:[1,0]
	v_pk_mul_f32 v[222:223], v[210:211], v[200:201] op_sel_hi:[1,0]
	v_exp_f32_e32 v216, v216
	v_exp_f32_e32 v217, v217
	v_exp_f32_e32 v218, v218
	v_exp_f32_e32 v219, v219
	v_exp_f32_e32 v220, v220
	v_exp_f32_e32 v221, v221
	v_exp_f32_e32 v222, v222
	v_exp_f32_e32 v223, v223
	v_pk_add_f32 v[216:217], v[216:217], v[200:201] op_sel:[0,1] op_sel_hi:[1,1]
	v_pk_add_f32 v[218:219], v[218:219], v[200:201] op_sel:[0,1] op_sel_hi:[1,1]
	v_pk_add_f32 v[220:221], v[220:221], v[200:201] op_sel:[0,1] op_sel_hi:[1,1]
	v_pk_add_f32 v[222:223], v[222:223], v[200:201] op_sel:[0,1] op_sel_hi:[1,1]
	v_rcp_f32_e32 v216, v216
	v_rcp_f32_e32 v217, v217
	v_rcp_f32_e32 v218, v218
	v_rcp_f32_e32 v219, v219
	v_rcp_f32_e32 v220, v220
	v_rcp_f32_e32 v221, v221
	v_rcp_f32_e32 v222, v222
	v_rcp_f32_e32 v223, v223
	v_cvt_pk_bf16_f32 v248, v216, v217
	v_cvt_pk_bf16_f32 v249, v218, v219
	v_cvt_pk_bf16_f32 v250, v220, v221
	v_cvt_pk_bf16_f32 v251, v222, v223
	v_add_u32_e32 v112, 48, v198
	v_mad_i64_i32 v[112:113], s[36:37], s0, v112, 0
	v_lshl_add_u64 v[112:113], v[112:113], 1, v[164:165]
	global_store_dwordx4 v[112:113], v[248:251], off nt
	s_cmp_gt_i32 s61, 1
	s_mov_b64 s[36:37], -1
	s_mov_b64 s[36:37], 0
	s_andn2_b64 vcc, exec, s[36:37]
	v_pk_fma_f32 v[204:205], v[40:41], v[138:139], v[56:57] op_sel:[0,1,0]
	v_pk_fma_f32 v[206:207], v[42:43], v[138:139], v[58:59] op_sel:[0,1,0]
	v_pk_fma_f32 v[208:209], v[32:33], v[138:139], v[44:45] op_sel:[0,1,0]
	v_pk_fma_f32 v[210:211], v[34:35], v[138:139], v[46:47] op_sel:[0,1,0]
	v_pk_fma_f32 v[204:205], v[108:109], v[138:139], v[204:205] op_sel_hi:[1,0,1]
	v_pk_fma_f32 v[206:207], v[110:111], v[138:139], v[206:207] op_sel_hi:[1,0,1]
	v_pk_fma_f32 v[208:209], v[104:105], v[138:139], v[208:209] op_sel_hi:[1,0,1]
	v_pk_fma_f32 v[210:211], v[106:107], v[138:139], v[210:211] op_sel_hi:[1,0,1]
	v_pk_mul_f32 v[216:217], v[204:205], v[200:201] op_sel_hi:[1,0]
	v_pk_mul_f32 v[218:219], v[206:207], v[200:201] op_sel_hi:[1,0]
	v_pk_mul_f32 v[220:221], v[208:209], v[200:201] op_sel_hi:[1,0]
	v_pk_mul_f32 v[222:223], v[210:211], v[200:201] op_sel_hi:[1,0]
	v_exp_f32_e32 v216, v216
	v_exp_f32_e32 v217, v217
	v_exp_f32_e32 v218, v218
	v_exp_f32_e32 v219, v219
	v_exp_f32_e32 v220, v220
	v_exp_f32_e32 v221, v221
	v_exp_f32_e32 v222, v222
	v_exp_f32_e32 v223, v223
	v_pk_add_f32 v[216:217], v[216:217], v[200:201] op_sel:[0,1] op_sel_hi:[1,1]
	v_pk_add_f32 v[218:219], v[218:219], v[200:201] op_sel:[0,1] op_sel_hi:[1,1]
	v_pk_add_f32 v[220:221], v[220:221], v[200:201] op_sel:[0,1] op_sel_hi:[1,1]
	v_pk_add_f32 v[222:223], v[222:223], v[200:201] op_sel:[0,1] op_sel_hi:[1,1]
	v_rcp_f32_e32 v216, v216
	v_rcp_f32_e32 v217, v217
	v_rcp_f32_e32 v218, v218
	v_rcp_f32_e32 v219, v219
	v_rcp_f32_e32 v220, v220
	v_rcp_f32_e32 v221, v221
	v_rcp_f32_e32 v222, v222
	v_rcp_f32_e32 v223, v223
	v_cvt_pk_bf16_f32 v224, v216, v217
	v_cvt_pk_bf16_f32 v225, v218, v219
	v_cvt_pk_bf16_f32 v226, v220, v221
	v_cvt_pk_bf16_f32 v227, v222, v223
	global_store_dwordx4 v[112:113], v[224:227], off offset:256 nt
	s_cmp_gt_i32 s61, 1
	s_mov_b64 s[36:37], -1
	s_mov_b64 s[36:37], 0
	s_andn2_b64 vcc, exec, s[36:37]
	v_pk_fma_f32 v[204:205], v[68:69], v[100:101], v[72:73] op_sel:[0,1,0]
	v_pk_fma_f32 v[206:207], v[70:71], v[100:101], v[74:75] op_sel:[0,1,0]
	v_pk_fma_f32 v[208:209], v[60:61], v[100:101], v[64:65] op_sel:[0,1,0]
	v_pk_fma_f32 v[210:211], v[62:63], v[100:101], v[66:67] op_sel:[0,1,0]
	v_pk_fma_f32 v[204:205], v[96:97], v[100:101], v[204:205] op_sel_hi:[1,0,1]
	v_pk_fma_f32 v[206:207], v[98:99], v[100:101], v[206:207] op_sel_hi:[1,0,1]
	v_pk_fma_f32 v[208:209], v[92:93], v[100:101], v[208:209] op_sel_hi:[1,0,1]
	v_pk_fma_f32 v[210:211], v[94:95], v[100:101], v[210:211] op_sel_hi:[1,0,1]
	v_pk_mul_f32 v[216:217], v[204:205], v[200:201] op_sel_hi:[1,0]
	v_pk_mul_f32 v[218:219], v[206:207], v[200:201] op_sel_hi:[1,0]
	v_pk_mul_f32 v[220:221], v[208:209], v[200:201] op_sel_hi:[1,0]
	v_pk_mul_f32 v[222:223], v[210:211], v[200:201] op_sel_hi:[1,0]
	v_exp_f32_e32 v216, v216
	v_exp_f32_e32 v217, v217
	v_exp_f32_e32 v218, v218
	v_exp_f32_e32 v219, v219
	v_exp_f32_e32 v220, v220
	v_exp_f32_e32 v221, v221
	v_exp_f32_e32 v222, v222
	v_exp_f32_e32 v223, v223
	v_pk_add_f32 v[216:217], v[216:217], v[200:201] op_sel:[0,1] op_sel_hi:[1,1]
	v_pk_add_f32 v[218:219], v[218:219], v[200:201] op_sel:[0,1] op_sel_hi:[1,1]
	v_pk_add_f32 v[220:221], v[220:221], v[200:201] op_sel:[0,1] op_sel_hi:[1,1]
	v_pk_add_f32 v[222:223], v[222:223], v[200:201] op_sel:[0,1] op_sel_hi:[1,1]
	v_rcp_f32_e32 v216, v216
	v_rcp_f32_e32 v217, v217
	v_rcp_f32_e32 v218, v218
	v_rcp_f32_e32 v219, v219
	v_rcp_f32_e32 v220, v220
	v_rcp_f32_e32 v221, v221
	v_rcp_f32_e32 v222, v222
	v_rcp_f32_e32 v223, v223
	v_cvt_pk_bf16_f32 v228, v216, v217
	v_cvt_pk_bf16_f32 v229, v218, v219
	v_cvt_pk_bf16_f32 v230, v220, v221
	v_cvt_pk_bf16_f32 v231, v222, v223
	v_add_u32_e32 v92, 0x80, v198
	v_mad_i64_i32 v[92:93], s[36:37], s0, v92, 0
	v_lshl_add_u64 v[92:93], v[92:93], 1, v[164:165]
	s_cmp_gt_i32 s61, 1
	s_mov_b64 s[36:37], -1
	global_store_dwordx4 v[92:93], v[228:231], off nt
	s_mov_b64 s[36:37], 0
	s_andn2_b64 vcc, exec, s[36:37]
	v_pk_fma_f32 v[204:205], v[40:41], v[100:101], v[56:57] op_sel:[0,1,0]
	v_pk_fma_f32 v[206:207], v[42:43], v[100:101], v[58:59] op_sel:[0,1,0]
	v_pk_fma_f32 v[208:209], v[32:33], v[100:101], v[44:45] op_sel:[0,1,0]
	v_pk_fma_f32 v[210:211], v[34:35], v[100:101], v[46:47] op_sel:[0,1,0]
	v_pk_fma_f32 v[204:205], v[88:89], v[100:101], v[204:205] op_sel_hi:[1,0,1]
	v_pk_fma_f32 v[206:207], v[90:91], v[100:101], v[206:207] op_sel_hi:[1,0,1]
	v_pk_fma_f32 v[208:209], v[84:85], v[100:101], v[208:209] op_sel_hi:[1,0,1]
	v_pk_fma_f32 v[210:211], v[86:87], v[100:101], v[210:211] op_sel_hi:[1,0,1]
	v_pk_mul_f32 v[216:217], v[204:205], v[200:201] op_sel_hi:[1,0]
	v_pk_mul_f32 v[218:219], v[206:207], v[200:201] op_sel_hi:[1,0]
	v_pk_mul_f32 v[220:221], v[208:209], v[200:201] op_sel_hi:[1,0]
	v_pk_mul_f32 v[222:223], v[210:211], v[200:201] op_sel_hi:[1,0]
	v_exp_f32_e32 v216, v216
	v_exp_f32_e32 v217, v217
	v_exp_f32_e32 v218, v218
	v_exp_f32_e32 v219, v219
	v_exp_f32_e32 v220, v220
	v_exp_f32_e32 v221, v221
	v_exp_f32_e32 v222, v222
	v_exp_f32_e32 v223, v223
	v_pk_add_f32 v[216:217], v[216:217], v[200:201] op_sel:[0,1] op_sel_hi:[1,1]
	v_pk_add_f32 v[218:219], v[218:219], v[200:201] op_sel:[0,1] op_sel_hi:[1,1]
	v_pk_add_f32 v[220:221], v[220:221], v[200:201] op_sel:[0,1] op_sel_hi:[1,1]
	v_pk_add_f32 v[222:223], v[222:223], v[200:201] op_sel:[0,1] op_sel_hi:[1,1]
	v_rcp_f32_e32 v216, v216
	v_rcp_f32_e32 v217, v217
	v_rcp_f32_e32 v218, v218
	v_rcp_f32_e32 v219, v219
	v_rcp_f32_e32 v220, v220
	v_rcp_f32_e32 v221, v221
	v_rcp_f32_e32 v222, v222
	v_rcp_f32_e32 v223, v223
	v_cvt_pk_bf16_f32 v232, v216, v217
	v_cvt_pk_bf16_f32 v233, v218, v219
	v_cvt_pk_bf16_f32 v234, v220, v221
	v_cvt_pk_bf16_f32 v235, v222, v223
	global_store_dwordx4 v[92:93], v[232:235], off offset:256 nt
	s_cmp_gt_i32 s61, 1
	s_mov_b64 s[36:37], -1
	s_mov_b64 s[36:37], 0
	s_andn2_b64 vcc, exec, s[36:37]
	v_pk_fma_f32 v[204:205], v[68:69], v[102:103], v[72:73] op_sel:[0,1,0]
	v_pk_fma_f32 v[206:207], v[70:71], v[102:103], v[74:75] op_sel:[0,1,0]
	v_pk_fma_f32 v[208:209], v[60:61], v[102:103], v[64:65] op_sel:[0,1,0]
	v_pk_fma_f32 v[210:211], v[62:63], v[102:103], v[66:67] op_sel:[0,1,0]
	v_pk_fma_f32 v[204:205], v[80:81], v[102:103], v[204:205] op_sel_hi:[1,0,1]
	v_pk_fma_f32 v[206:207], v[82:83], v[102:103], v[206:207] op_sel_hi:[1,0,1]
	v_pk_fma_f32 v[208:209], v[76:77], v[102:103], v[208:209] op_sel_hi:[1,0,1]
	v_pk_fma_f32 v[210:211], v[78:79], v[102:103], v[210:211] op_sel_hi:[1,0,1]
	v_pk_mul_f32 v[216:217], v[204:205], v[200:201] op_sel_hi:[1,0]
	v_pk_mul_f32 v[218:219], v[206:207], v[200:201] op_sel_hi:[1,0]
	v_pk_mul_f32 v[220:221], v[208:209], v[200:201] op_sel_hi:[1,0]
	v_pk_mul_f32 v[222:223], v[210:211], v[200:201] op_sel_hi:[1,0]
	v_exp_f32_e32 v216, v216
	v_exp_f32_e32 v217, v217
	v_exp_f32_e32 v218, v218
	v_exp_f32_e32 v219, v219
	v_exp_f32_e32 v220, v220
	v_exp_f32_e32 v221, v221
	v_exp_f32_e32 v222, v222
	v_exp_f32_e32 v223, v223
	v_pk_add_f32 v[216:217], v[216:217], v[200:201] op_sel:[0,1] op_sel_hi:[1,1]
	v_pk_add_f32 v[218:219], v[218:219], v[200:201] op_sel:[0,1] op_sel_hi:[1,1]
	v_pk_add_f32 v[220:221], v[220:221], v[200:201] op_sel:[0,1] op_sel_hi:[1,1]
	v_pk_add_f32 v[222:223], v[222:223], v[200:201] op_sel:[0,1] op_sel_hi:[1,1]
	v_rcp_f32_e32 v216, v216
	v_rcp_f32_e32 v217, v217
	v_rcp_f32_e32 v218, v218
	v_rcp_f32_e32 v219, v219
	v_rcp_f32_e32 v220, v220
	v_rcp_f32_e32 v221, v221
	v_rcp_f32_e32 v222, v222
	v_rcp_f32_e32 v223, v223
	v_cvt_pk_bf16_f32 v236, v216, v217
	v_cvt_pk_bf16_f32 v237, v218, v219
	v_cvt_pk_bf16_f32 v238, v220, v221
	v_cvt_pk_bf16_f32 v239, v222, v223
	v_add_u32_e32 v76, 0x90, v198
	v_mad_i64_i32 v[76:77], s[36:37], s0, v76, 0
	v_lshl_add_u64 v[76:77], v[76:77], 1, v[164:165]
	global_store_dwordx4 v[76:77], v[236:239], off nt
	s_cmp_gt_i32 s61, 1
	s_mov_b64 s[36:37], -1
	s_mov_b64 s[36:37], 0
	s_andn2_b64 vcc, exec, s[36:37]
	v_pk_fma_f32 v[204:205], v[40:41], v[102:103], v[56:57] op_sel:[0,1,0]
	v_pk_fma_f32 v[206:207], v[42:43], v[102:103], v[58:59] op_sel:[0,1,0]
	v_pk_fma_f32 v[208:209], v[32:33], v[102:103], v[44:45] op_sel:[0,1,0]
	v_pk_fma_f32 v[210:211], v[34:35], v[102:103], v[46:47] op_sel:[0,1,0]
	v_pk_fma_f32 v[204:205], v[52:53], v[102:103], v[204:205] op_sel_hi:[1,0,1]
	v_pk_fma_f32 v[206:207], v[54:55], v[102:103], v[206:207] op_sel_hi:[1,0,1]
	v_pk_fma_f32 v[208:209], v[36:37], v[102:103], v[208:209] op_sel_hi:[1,0,1]
	v_pk_fma_f32 v[210:211], v[38:39], v[102:103], v[210:211] op_sel_hi:[1,0,1]
	v_pk_mul_f32 v[216:217], v[204:205], v[200:201] op_sel_hi:[1,0]
	v_pk_mul_f32 v[218:219], v[206:207], v[200:201] op_sel_hi:[1,0]
	v_pk_mul_f32 v[220:221], v[208:209], v[200:201] op_sel_hi:[1,0]
	v_pk_mul_f32 v[222:223], v[210:211], v[200:201] op_sel_hi:[1,0]
	v_exp_f32_e32 v216, v216
	v_exp_f32_e32 v217, v217
	v_exp_f32_e32 v218, v218
	v_exp_f32_e32 v219, v219
	v_exp_f32_e32 v220, v220
	v_exp_f32_e32 v221, v221
	v_exp_f32_e32 v222, v222
	v_exp_f32_e32 v223, v223
	v_pk_add_f32 v[216:217], v[216:217], v[200:201] op_sel:[0,1] op_sel_hi:[1,1]
	v_pk_add_f32 v[218:219], v[218:219], v[200:201] op_sel:[0,1] op_sel_hi:[1,1]
	v_pk_add_f32 v[220:221], v[220:221], v[200:201] op_sel:[0,1] op_sel_hi:[1,1]
	v_pk_add_f32 v[222:223], v[222:223], v[200:201] op_sel:[0,1] op_sel_hi:[1,1]
	v_rcp_f32_e32 v216, v216
	v_rcp_f32_e32 v217, v217
	v_rcp_f32_e32 v218, v218
	v_rcp_f32_e32 v219, v219
	v_rcp_f32_e32 v220, v220
	v_rcp_f32_e32 v221, v221
	v_rcp_f32_e32 v222, v222
	v_rcp_f32_e32 v223, v223
	v_cvt_pk_bf16_f32 v240, v216, v217
	v_cvt_pk_bf16_f32 v241, v218, v219
	v_cvt_pk_bf16_f32 v242, v220, v221
	v_cvt_pk_bf16_f32 v243, v222, v223
	global_store_dwordx4 v[76:77], v[240:243], off offset:256 nt
	s_cmp_gt_i32 s61, 1
	s_mov_b64 s[36:37], -1
	s_mov_b64 s[36:37], 0
	s_andn2_b64 vcc, exec, s[36:37]
	v_pk_fma_f32 v[204:205], v[68:69], v[48:49], v[72:73] op_sel:[0,1,0]
	v_pk_fma_f32 v[206:207], v[70:71], v[48:49], v[74:75] op_sel:[0,1,0]
	v_pk_fma_f32 v[208:209], v[60:61], v[48:49], v[64:65] op_sel:[0,1,0]
	v_pk_fma_f32 v[210:211], v[62:63], v[48:49], v[66:67] op_sel:[0,1,0]
	v_pk_fma_f32 v[204:205], v[28:29], v[48:49], v[204:205] op_sel_hi:[1,0,1]
	v_pk_fma_f32 v[206:207], v[30:31], v[48:49], v[206:207] op_sel_hi:[1,0,1]
	v_pk_fma_f32 v[208:209], v[24:25], v[48:49], v[208:209] op_sel_hi:[1,0,1]
	v_pk_fma_f32 v[210:211], v[26:27], v[48:49], v[210:211] op_sel_hi:[1,0,1]
	v_pk_mul_f32 v[216:217], v[204:205], v[200:201] op_sel_hi:[1,0]
	v_pk_mul_f32 v[218:219], v[206:207], v[200:201] op_sel_hi:[1,0]
	v_pk_mul_f32 v[220:221], v[208:209], v[200:201] op_sel_hi:[1,0]
	v_pk_mul_f32 v[222:223], v[210:211], v[200:201] op_sel_hi:[1,0]
	v_exp_f32_e32 v216, v216
	v_exp_f32_e32 v217, v217
	v_exp_f32_e32 v218, v218
	v_exp_f32_e32 v219, v219
	v_exp_f32_e32 v220, v220
	v_exp_f32_e32 v221, v221
	v_exp_f32_e32 v222, v222
	v_exp_f32_e32 v223, v223
	v_pk_add_f32 v[216:217], v[216:217], v[200:201] op_sel:[0,1] op_sel_hi:[1,1]
	v_pk_add_f32 v[218:219], v[218:219], v[200:201] op_sel:[0,1] op_sel_hi:[1,1]
	v_pk_add_f32 v[220:221], v[220:221], v[200:201] op_sel:[0,1] op_sel_hi:[1,1]
	v_pk_add_f32 v[222:223], v[222:223], v[200:201] op_sel:[0,1] op_sel_hi:[1,1]
	v_rcp_f32_e32 v216, v216
	v_rcp_f32_e32 v217, v217
	v_rcp_f32_e32 v218, v218
	v_rcp_f32_e32 v219, v219
	v_rcp_f32_e32 v220, v220
	v_rcp_f32_e32 v221, v221
	v_rcp_f32_e32 v222, v222
	v_rcp_f32_e32 v223, v223
	v_cvt_pk_bf16_f32 v244, v216, v217
	v_cvt_pk_bf16_f32 v245, v218, v219
	v_cvt_pk_bf16_f32 v246, v220, v221
	v_cvt_pk_bf16_f32 v247, v222, v223
	v_add_u32_e32 v24, 0xa0, v198
	v_mad_i64_i32 v[24:25], s[36:37], s0, v24, 0
	v_lshl_add_u64 v[24:25], v[24:25], 1, v[164:165]
	s_cmp_gt_i32 s61, 1
	s_mov_b64 s[36:37], -1
	global_store_dwordx4 v[24:25], v[244:247], off nt
	s_mov_b64 s[36:37], 0
	s_andn2_b64 vcc, exec, s[36:37]
	v_pk_fma_f32 v[204:205], v[40:41], v[48:49], v[56:57] op_sel:[0,1,0]
	v_pk_fma_f32 v[206:207], v[42:43], v[48:49], v[58:59] op_sel:[0,1,0]
	v_pk_fma_f32 v[208:209], v[32:33], v[48:49], v[44:45] op_sel:[0,1,0]
	v_pk_fma_f32 v[210:211], v[34:35], v[48:49], v[46:47] op_sel:[0,1,0]
	v_pk_fma_f32 v[204:205], v[20:21], v[48:49], v[204:205] op_sel_hi:[1,0,1]
	v_pk_fma_f32 v[206:207], v[22:23], v[48:49], v[206:207] op_sel_hi:[1,0,1]
	v_pk_fma_f32 v[208:209], v[16:17], v[48:49], v[208:209] op_sel_hi:[1,0,1]
	v_pk_fma_f32 v[210:211], v[18:19], v[48:49], v[210:211] op_sel_hi:[1,0,1]
	v_pk_mul_f32 v[216:217], v[204:205], v[200:201] op_sel_hi:[1,0]
	v_pk_mul_f32 v[218:219], v[206:207], v[200:201] op_sel_hi:[1,0]
	v_pk_mul_f32 v[220:221], v[208:209], v[200:201] op_sel_hi:[1,0]
	v_pk_mul_f32 v[222:223], v[210:211], v[200:201] op_sel_hi:[1,0]
	v_exp_f32_e32 v216, v216
	v_exp_f32_e32 v217, v217
	v_exp_f32_e32 v218, v218
	v_exp_f32_e32 v219, v219
	v_exp_f32_e32 v220, v220
	v_exp_f32_e32 v221, v221
	v_exp_f32_e32 v222, v222
	v_exp_f32_e32 v223, v223
	v_pk_add_f32 v[216:217], v[216:217], v[200:201] op_sel:[0,1] op_sel_hi:[1,1]
	v_pk_add_f32 v[218:219], v[218:219], v[200:201] op_sel:[0,1] op_sel_hi:[1,1]
	v_pk_add_f32 v[220:221], v[220:221], v[200:201] op_sel:[0,1] op_sel_hi:[1,1]
	v_pk_add_f32 v[222:223], v[222:223], v[200:201] op_sel:[0,1] op_sel_hi:[1,1]
	v_rcp_f32_e32 v216, v216
	v_rcp_f32_e32 v217, v217
	v_rcp_f32_e32 v218, v218
	v_rcp_f32_e32 v219, v219
	v_rcp_f32_e32 v220, v220
	v_rcp_f32_e32 v221, v221
	v_rcp_f32_e32 v222, v222
	v_rcp_f32_e32 v223, v223
	v_cvt_pk_bf16_f32 v248, v216, v217
	v_cvt_pk_bf16_f32 v249, v218, v219
	v_cvt_pk_bf16_f32 v250, v220, v221
	v_cvt_pk_bf16_f32 v251, v222, v223
	global_store_dwordx4 v[24:25], v[248:251], off offset:256 nt
	s_cmp_gt_i32 s61, 1
	s_mov_b64 s[36:37], -1
	s_mov_b64 s[36:37], 0
	s_andn2_b64 vcc, exec, s[36:37]
	v_pk_fma_f32 v[204:205], v[68:69], v[50:51], v[72:73] op_sel:[0,1,0]
	v_pk_fma_f32 v[206:207], v[70:71], v[50:51], v[74:75] op_sel:[0,1,0]
	v_pk_fma_f32 v[208:209], v[60:61], v[50:51], v[64:65] op_sel:[0,1,0]
	v_pk_fma_f32 v[210:211], v[62:63], v[50:51], v[66:67] op_sel:[0,1,0]
	v_pk_fma_f32 v[204:205], v[12:13], v[50:51], v[204:205] op_sel_hi:[1,0,1]
	v_pk_fma_f32 v[206:207], v[14:15], v[50:51], v[206:207] op_sel_hi:[1,0,1]
	v_pk_fma_f32 v[208:209], v[8:9], v[50:51], v[208:209] op_sel_hi:[1,0,1]
	v_pk_fma_f32 v[210:211], v[10:11], v[50:51], v[210:211] op_sel_hi:[1,0,1]
	v_pk_mul_f32 v[216:217], v[204:205], v[200:201] op_sel_hi:[1,0]
	v_pk_mul_f32 v[218:219], v[206:207], v[200:201] op_sel_hi:[1,0]
	v_pk_mul_f32 v[220:221], v[208:209], v[200:201] op_sel_hi:[1,0]
	v_pk_mul_f32 v[222:223], v[210:211], v[200:201] op_sel_hi:[1,0]
	v_exp_f32_e32 v216, v216
	v_exp_f32_e32 v217, v217
	v_exp_f32_e32 v218, v218
	v_exp_f32_e32 v219, v219
	v_exp_f32_e32 v220, v220
	v_exp_f32_e32 v221, v221
	v_exp_f32_e32 v222, v222
	v_exp_f32_e32 v223, v223
	v_pk_add_f32 v[216:217], v[216:217], v[200:201] op_sel:[0,1] op_sel_hi:[1,1]
	v_pk_add_f32 v[218:219], v[218:219], v[200:201] op_sel:[0,1] op_sel_hi:[1,1]
	v_pk_add_f32 v[220:221], v[220:221], v[200:201] op_sel:[0,1] op_sel_hi:[1,1]
	v_pk_add_f32 v[222:223], v[222:223], v[200:201] op_sel:[0,1] op_sel_hi:[1,1]
	v_rcp_f32_e32 v216, v216
	v_rcp_f32_e32 v217, v217
	v_rcp_f32_e32 v218, v218
	v_rcp_f32_e32 v219, v219
	v_rcp_f32_e32 v220, v220
	v_rcp_f32_e32 v221, v221
	v_rcp_f32_e32 v222, v222
	v_rcp_f32_e32 v223, v223
	v_cvt_pk_bf16_f32 v224, v216, v217
	v_cvt_pk_bf16_f32 v225, v218, v219
	v_cvt_pk_bf16_f32 v226, v220, v221
	v_cvt_pk_bf16_f32 v227, v222, v223
	v_add_u32_e32 v8, 0xb0, v198
	v_mad_i64_i32 v[8:9], s[36:37], s0, v8, 0
	v_lshl_add_u64 v[8:9], v[8:9], 1, v[164:165]
	global_store_dwordx4 v[8:9], v[224:227], off nt
	s_cmp_gt_i32 s61, 1
	s_mov_b64 s[36:37], -1
	s_mov_b64 s[36:37], 0
	s_andn2_b64 vcc, exec, s[36:37]
	s_andn2_b64 vcc, exec, s[10:11]
	s_mov_b64 s[10:11], -1
	v_pk_fma_f32 v[204:205], v[40:41], v[50:51], v[56:57] op_sel:[0,1,0]
	v_pk_fma_f32 v[206:207], v[42:43], v[50:51], v[58:59] op_sel:[0,1,0]
	v_pk_fma_f32 v[208:209], v[32:33], v[50:51], v[44:45] op_sel:[0,1,0]
	v_pk_fma_f32 v[210:211], v[34:35], v[50:51], v[46:47] op_sel:[0,1,0]
	v_pk_fma_f32 v[204:205], v[4:5], v[50:51], v[204:205] op_sel_hi:[1,0,1]
	v_pk_fma_f32 v[206:207], v[6:7], v[50:51], v[206:207] op_sel_hi:[1,0,1]
	v_pk_fma_f32 v[208:209], v[0:1], v[50:51], v[208:209] op_sel_hi:[1,0,1]
	v_pk_fma_f32 v[210:211], v[2:3], v[50:51], v[210:211] op_sel_hi:[1,0,1]
	v_pk_mul_f32 v[216:217], v[204:205], v[200:201] op_sel_hi:[1,0]
	v_pk_mul_f32 v[218:219], v[206:207], v[200:201] op_sel_hi:[1,0]
	v_pk_mul_f32 v[220:221], v[208:209], v[200:201] op_sel_hi:[1,0]
	v_pk_mul_f32 v[222:223], v[210:211], v[200:201] op_sel_hi:[1,0]
	v_exp_f32_e32 v216, v216
	v_exp_f32_e32 v217, v217
	v_exp_f32_e32 v218, v218
	v_exp_f32_e32 v219, v219
	v_exp_f32_e32 v220, v220
	v_exp_f32_e32 v221, v221
	v_exp_f32_e32 v222, v222
	v_exp_f32_e32 v223, v223
	v_pk_add_f32 v[216:217], v[216:217], v[200:201] op_sel:[0,1] op_sel_hi:[1,1]
	v_pk_add_f32 v[218:219], v[218:219], v[200:201] op_sel:[0,1] op_sel_hi:[1,1]
	v_pk_add_f32 v[220:221], v[220:221], v[200:201] op_sel:[0,1] op_sel_hi:[1,1]
	v_pk_add_f32 v[222:223], v[222:223], v[200:201] op_sel:[0,1] op_sel_hi:[1,1]
	v_rcp_f32_e32 v216, v216
	v_rcp_f32_e32 v217, v217
	v_rcp_f32_e32 v218, v218
	v_rcp_f32_e32 v219, v219
	v_rcp_f32_e32 v220, v220
	v_rcp_f32_e32 v221, v221
	v_rcp_f32_e32 v222, v222
	v_rcp_f32_e32 v223, v223
	v_cvt_pk_bf16_f32 v228, v216, v217
	v_cvt_pk_bf16_f32 v229, v218, v219
	v_cvt_pk_bf16_f32 v230, v220, v221
	v_cvt_pk_bf16_f32 v231, v222, v223
	global_store_dwordx4 v[8:9], v[228:231], off offset:256 nt

.Le1m2_26:
	v_mov_b32_e32 v200, 0xbfb8aa3b
	v_mov_b32_e32 v201, 1.0
	s_cmp_eq_u32 s36, s61
	s_movk_i32 s0, 0x200
	s_cselect_b32 s0, s0, 0x300
	s_cmp_lg_u32 s36, s60
	v_mov_b32_e32 v44, v192
	v_mov_b32_e32 v198, v193
	s_cselect_b32 s0, s0, 0x100
	s_cmp_lg_u32 s36, s19
	s_cselect_b32 s0, s0, 0
	v_lshl_add_u32 v45, v198, 5, s73
	v_add_u32_e32 v199, s68, v44
	ds_read_b128 v[68:71], v45
	ds_read_b128 v[60:63], v45 offset:16
	ds_read_b128 v[72:75], v45 offset:256
	ds_read_b128 v[64:67], v45 offset:272
	ds_read_b128 v[40:43], v45 offset:128
	ds_read_b128 v[32:35], v45 offset:144
	v_add_u32_e32 v44, s0, v199
	v_lshl_add_u32 v48, v44, 3, v197
	ds_read2_b64 v[172:175], v48 offset1:16
	ds_read_b128 v[56:59], v45 offset:384
	ds_read_b128 v[44:47], v45 offset:400
	ds_read2_b64 v[136:139], v48 offset0:32 offset1:48
	ds_read2_b64 v[100:103], v48 offset0:128 offset1:144
	ds_read2_b64 v[48:51], v48 offset0:160 offset1:176
	s_waitcnt lgkmcnt(0)
	s_cmp_gt_i32 s23, 1
	s_mov_b64 s[46:47], -1
	s_mov_b64 s[46:47], 0
	s_andn2_b64 vcc, exec, s[46:47]
	s_add_i32 s0, s48, 0xfffff400
	s_lshl_b64 s[46:47], s[0:1], 1
	s_add_u32 s0, s56, s46
	s_addc_u32 s25, s57, s47
	s_ashr_i32 s49, s48, 31
	s_lshl_b64 s[46:47], s[48:49], 1
	s_add_u32 s37, s42, s46
	s_addc_u32 s46, s43, s47
	s_cmp_lt_i32 s40, 12
	s_cselect_b32 s0, s37, s0
	v_pk_fma_f32 v[204:205], v[68:69], v[172:173], v[72:73] op_sel:[0,1,0]
	v_pk_fma_f32 v[206:207], v[70:71], v[172:173], v[74:75] op_sel:[0,1,0]
	v_pk_fma_f32 v[208:209], v[60:61], v[172:173], v[64:65] op_sel:[0,1,0]
	v_pk_fma_f32 v[210:211], v[62:63], v[172:173], v[66:67] op_sel:[0,1,0]
	v_pk_fma_f32 v[204:205], v[168:169], v[172:173], v[204:205] op_sel_hi:[1,0,1]
	v_pk_fma_f32 v[206:207], v[170:171], v[172:173], v[206:207] op_sel_hi:[1,0,1]
	v_pk_fma_f32 v[208:209], v[164:165], v[172:173], v[208:209] op_sel_hi:[1,0,1]
	v_pk_fma_f32 v[210:211], v[166:167], v[172:173], v[210:211] op_sel_hi:[1,0,1]
	v_pk_mul_f32 v[216:217], v[204:205], v[200:201] op_sel_hi:[1,0]
	v_pk_mul_f32 v[218:219], v[206:207], v[200:201] op_sel_hi:[1,0]
	v_pk_mul_f32 v[220:221], v[208:209], v[200:201] op_sel_hi:[1,0]
	v_pk_mul_f32 v[222:223], v[210:211], v[200:201] op_sel_hi:[1,0]
	v_exp_f32_e32 v216, v216
	v_exp_f32_e32 v217, v217
	v_exp_f32_e32 v218, v218
	v_exp_f32_e32 v219, v219
	v_exp_f32_e32 v220, v220
	v_exp_f32_e32 v221, v221
	v_exp_f32_e32 v222, v222
	v_exp_f32_e32 v223, v223
	v_pk_add_f32 v[216:217], v[216:217], v[200:201] op_sel:[0,1] op_sel_hi:[1,1]
	v_pk_add_f32 v[218:219], v[218:219], v[200:201] op_sel:[0,1] op_sel_hi:[1,1]
	v_pk_add_f32 v[220:221], v[220:221], v[200:201] op_sel:[0,1] op_sel_hi:[1,1]
	v_pk_add_f32 v[222:223], v[222:223], v[200:201] op_sel:[0,1] op_sel_hi:[1,1]
	v_rcp_f32_e32 v216, v216
	v_rcp_f32_e32 v217, v217
	v_rcp_f32_e32 v218, v218
	v_rcp_f32_e32 v219, v219
	v_rcp_f32_e32 v220, v220
	v_rcp_f32_e32 v221, v221
	v_rcp_f32_e32 v222, v222
	v_rcp_f32_e32 v223, v223
	v_cvt_pk_bf16_f32 v224, v216, v217
	v_cvt_pk_bf16_f32 v225, v218, v219
	v_cvt_pk_bf16_f32 v226, v220, v221
	v_cvt_pk_bf16_f32 v227, v222, v223
	v_lshl_add_u32 v164, v198, 3, s69
	s_cselect_b32 s25, s46, s25
	v_mov_b32_e32 v166, s0
	s_movk_i32 s0, 0xc00
	v_mov_b32_e32 v167, s25
	s_cselect_b32 s0, s0, 0x800
	v_ashrrev_i32_e32 v165, 31, v164
	v_lshl_add_u32 v198, s36, 8, v199
	v_lshl_add_u64 v[164:165], v[164:165], 1, v[166:167]
	v_mad_i64_i32 v[166:167], s[36:37], s0, v198, 0
	v_lshl_add_u64 v[166:167], v[166:167], 1, v[164:165]
	s_cmp_gt_i32 s23, 1
	s_mov_b64 s[36:37], -1
	global_store_dwordx4 v[166:167], v[224:227], off nt
	s_mov_b64 s[36:37], 0
	s_andn2_b64 vcc, exec, s[36:37]
	v_pk_fma_f32 v[204:205], v[40:41], v[172:173], v[56:57] op_sel:[0,1,0]
	v_pk_fma_f32 v[206:207], v[42:43], v[172:173], v[58:59] op_sel:[0,1,0]
	v_pk_fma_f32 v[208:209], v[32:33], v[172:173], v[44:45] op_sel:[0,1,0]
	v_pk_fma_f32 v[210:211], v[34:35], v[172:173], v[46:47] op_sel:[0,1,0]
	v_pk_fma_f32 v[204:205], v[160:161], v[172:173], v[204:205] op_sel_hi:[1,0,1]
	v_pk_fma_f32 v[206:207], v[162:163], v[172:173], v[206:207] op_sel_hi:[1,0,1]
	v_pk_fma_f32 v[208:209], v[156:157], v[172:173], v[208:209] op_sel_hi:[1,0,1]
	v_pk_fma_f32 v[210:211], v[158:159], v[172:173], v[210:211] op_sel_hi:[1,0,1]
	v_pk_mul_f32 v[216:217], v[204:205], v[200:201] op_sel_hi:[1,0]
	v_pk_mul_f32 v[218:219], v[206:207], v[200:201] op_sel_hi:[1,0]
	v_pk_mul_f32 v[220:221], v[208:209], v[200:201] op_sel_hi:[1,0]
	v_pk_mul_f32 v[222:223], v[210:211], v[200:201] op_sel_hi:[1,0]
	v_exp_f32_e32 v216, v216
	v_exp_f32_e32 v217, v217
	v_exp_f32_e32 v218, v218
	v_exp_f32_e32 v219, v219
	v_exp_f32_e32 v220, v220
	v_exp_f32_e32 v221, v221
	v_exp_f32_e32 v222, v222
	v_exp_f32_e32 v223, v223
	v_pk_add_f32 v[216:217], v[216:217], v[200:201] op_sel:[0,1] op_sel_hi:[1,1]
	v_pk_add_f32 v[218:219], v[218:219], v[200:201] op_sel:[0,1] op_sel_hi:[1,1]
	v_pk_add_f32 v[220:221], v[220:221], v[200:201] op_sel:[0,1] op_sel_hi:[1,1]
	v_pk_add_f32 v[222:223], v[222:223], v[200:201] op_sel:[0,1] op_sel_hi:[1,1]
	v_rcp_f32_e32 v216, v216
	v_rcp_f32_e32 v217, v217
	v_rcp_f32_e32 v218, v218
	v_rcp_f32_e32 v219, v219
	v_rcp_f32_e32 v220, v220
	v_rcp_f32_e32 v221, v221
	v_rcp_f32_e32 v222, v222
	v_rcp_f32_e32 v223, v223
	v_cvt_pk_bf16_f32 v228, v216, v217
	v_cvt_pk_bf16_f32 v229, v218, v219
	v_cvt_pk_bf16_f32 v230, v220, v221
	v_cvt_pk_bf16_f32 v231, v222, v223
	global_store_dwordx4 v[166:167], v[228:231], off offset:256 nt
	s_cmp_gt_i32 s23, 1
	s_mov_b64 s[36:37], -1
	s_mov_b64 s[36:37], 0
	s_andn2_b64 vcc, exec, s[36:37]
	v_pk_fma_f32 v[204:205], v[68:69], v[174:175], v[72:73] op_sel:[0,1,0]
	v_pk_fma_f32 v[206:207], v[70:71], v[174:175], v[74:75] op_sel:[0,1,0]
	v_pk_fma_f32 v[208:209], v[60:61], v[174:175], v[64:65] op_sel:[0,1,0]
	v_pk_fma_f32 v[210:211], v[62:63], v[174:175], v[66:67] op_sel:[0,1,0]
	v_pk_fma_f32 v[204:205], v[152:153], v[174:175], v[204:205] op_sel_hi:[1,0,1]
	v_pk_fma_f32 v[206:207], v[154:155], v[174:175], v[206:207] op_sel_hi:[1,0,1]
	v_pk_fma_f32 v[208:209], v[148:149], v[174:175], v[208:209] op_sel_hi:[1,0,1]
	v_pk_fma_f32 v[210:211], v[150:151], v[174:175], v[210:211] op_sel_hi:[1,0,1]
	v_pk_mul_f32 v[216:217], v[204:205], v[200:201] op_sel_hi:[1,0]
	v_pk_mul_f32 v[218:219], v[206:207], v[200:201] op_sel_hi:[1,0]
	v_pk_mul_f32 v[220:221], v[208:209], v[200:201] op_sel_hi:[1,0]
	v_pk_mul_f32 v[222:223], v[210:211], v[200:201] op_sel_hi:[1,0]
	v_exp_f32_e32 v216, v216
	v_exp_f32_e32 v217, v217
	v_exp_f32_e32 v218, v218
	v_exp_f32_e32 v219, v219
	v_exp_f32_e32 v220, v220
	v_exp_f32_e32 v221, v221
	v_exp_f32_e32 v222, v222
	v_exp_f32_e32 v223, v223
	v_pk_add_f32 v[216:217], v[216:217], v[200:201] op_sel:[0,1] op_sel_hi:[1,1]
	v_pk_add_f32 v[218:219], v[218:219], v[200:201] op_sel:[0,1] op_sel_hi:[1,1]
	v_pk_add_f32 v[220:221], v[220:221], v[200:201] op_sel:[0,1] op_sel_hi:[1,1]
	v_pk_add_f32 v[222:223], v[222:223], v[200:201] op_sel:[0,1] op_sel_hi:[1,1]
	v_rcp_f32_e32 v216, v216
	v_rcp_f32_e32 v217, v217
	v_rcp_f32_e32 v218, v218
	v_rcp_f32_e32 v219, v219
	v_rcp_f32_e32 v220, v220
	v_rcp_f32_e32 v221, v221
	v_rcp_f32_e32 v222, v222
	v_rcp_f32_e32 v223, v223
	v_cvt_pk_bf16_f32 v232, v216, v217
	v_cvt_pk_bf16_f32 v233, v218, v219
	v_cvt_pk_bf16_f32 v234, v220, v221
	v_cvt_pk_bf16_f32 v235, v222, v223
	v_add_u32_e32 v148, 16, v198
	v_mad_i64_i32 v[148:149], s[36:37], s0, v148, 0
	v_lshl_add_u64 v[148:149], v[148:149], 1, v[164:165]
	global_store_dwordx4 v[148:149], v[232:235], off nt
	s_cmp_gt_i32 s23, 1
	s_mov_b64 s[36:37], -1
	s_mov_b64 s[36:37], 0
	s_andn2_b64 vcc, exec, s[36:37]
	v_pk_fma_f32 v[204:205], v[40:41], v[174:175], v[56:57] op_sel:[0,1,0]
	v_pk_fma_f32 v[206:207], v[42:43], v[174:175], v[58:59] op_sel:[0,1,0]
	v_pk_fma_f32 v[208:209], v[32:33], v[174:175], v[44:45] op_sel:[0,1,0]
	v_pk_fma_f32 v[210:211], v[34:35], v[174:175], v[46:47] op_sel:[0,1,0]
	v_pk_fma_f32 v[204:205], v[144:145], v[174:175], v[204:205] op_sel_hi:[1,0,1]
	v_pk_fma_f32 v[206:207], v[146:147], v[174:175], v[206:207] op_sel_hi:[1,0,1]
	v_pk_fma_f32 v[208:209], v[140:141], v[174:175], v[208:209] op_sel_hi:[1,0,1]
	v_pk_fma_f32 v[210:211], v[142:143], v[174:175], v[210:211] op_sel_hi:[1,0,1]
	v_pk_mul_f32 v[216:217], v[204:205], v[200:201] op_sel_hi:[1,0]
	v_pk_mul_f32 v[218:219], v[206:207], v[200:201] op_sel_hi:[1,0]
	v_pk_mul_f32 v[220:221], v[208:209], v[200:201] op_sel_hi:[1,0]
	v_pk_mul_f32 v[222:223], v[210:211], v[200:201] op_sel_hi:[1,0]
	v_exp_f32_e32 v216, v216
	v_exp_f32_e32 v217, v217
	v_exp_f32_e32 v218, v218
	v_exp_f32_e32 v219, v219
	v_exp_f32_e32 v220, v220
	v_exp_f32_e32 v221, v221
	v_exp_f32_e32 v222, v222
	v_exp_f32_e32 v223, v223
	v_pk_add_f32 v[216:217], v[216:217], v[200:201] op_sel:[0,1] op_sel_hi:[1,1]
	v_pk_add_f32 v[218:219], v[218:219], v[200:201] op_sel:[0,1] op_sel_hi:[1,1]
	v_pk_add_f32 v[220:221], v[220:221], v[200:201] op_sel:[0,1] op_sel_hi:[1,1]
	v_pk_add_f32 v[222:223], v[222:223], v[200:201] op_sel:[0,1] op_sel_hi:[1,1]
	v_rcp_f32_e32 v216, v216
	v_rcp_f32_e32 v217, v217
	v_rcp_f32_e32 v218, v218
	v_rcp_f32_e32 v219, v219
	v_rcp_f32_e32 v220, v220
	v_rcp_f32_e32 v221, v221
	v_rcp_f32_e32 v222, v222
	v_rcp_f32_e32 v223, v223
	v_cvt_pk_bf16_f32 v236, v216, v217
	v_cvt_pk_bf16_f32 v237, v218, v219
	v_cvt_pk_bf16_f32 v238, v220, v221
	v_cvt_pk_bf16_f32 v239, v222, v223
	global_store_dwordx4 v[148:149], v[236:239], off offset:256 nt
	s_cmp_gt_i32 s23, 1
	s_mov_b64 s[36:37], -1
	s_mov_b64 s[36:37], 0
	s_andn2_b64 vcc, exec, s[36:37]
	v_pk_fma_f32 v[204:205], v[68:69], v[136:137], v[72:73] op_sel:[0,1,0]
	v_pk_fma_f32 v[206:207], v[70:71], v[136:137], v[74:75] op_sel:[0,1,0]
	v_pk_fma_f32 v[208:209], v[60:61], v[136:137], v[64:65] op_sel:[0,1,0]
	v_pk_fma_f32 v[210:211], v[62:63], v[136:137], v[66:67] op_sel:[0,1,0]
	v_pk_fma_f32 v[204:205], v[132:133], v[136:137], v[204:205] op_sel_hi:[1,0,1]
	v_pk_fma_f32 v[206:207], v[134:135], v[136:137], v[206:207] op_sel_hi:[1,0,1]
	v_pk_fma_f32 v[208:209], v[128:129], v[136:137], v[208:209] op_sel_hi:[1,0,1]
	v_pk_fma_f32 v[210:211], v[130:131], v[136:137], v[210:211] op_sel_hi:[1,0,1]
	v_pk_mul_f32 v[216:217], v[204:205], v[200:201] op_sel_hi:[1,0]
	v_pk_mul_f32 v[218:219], v[206:207], v[200:201] op_sel_hi:[1,0]
	v_pk_mul_f32 v[220:221], v[208:209], v[200:201] op_sel_hi:[1,0]
	v_pk_mul_f32 v[222:223], v[210:211], v[200:201] op_sel_hi:[1,0]
	v_exp_f32_e32 v216, v216
	v_exp_f32_e32 v217, v217
	v_exp_f32_e32 v218, v218
	v_exp_f32_e32 v219, v219
	v_exp_f32_e32 v220, v220
	v_exp_f32_e32 v221, v221
	v_exp_f32_e32 v222, v222
	v_exp_f32_e32 v223, v223
	v_pk_add_f32 v[216:217], v[216:217], v[200:201] op_sel:[0,1] op_sel_hi:[1,1]
	v_pk_add_f32 v[218:219], v[218:219], v[200:201] op_sel:[0,1] op_sel_hi:[1,1]
	v_pk_add_f32 v[220:221], v[220:221], v[200:201] op_sel:[0,1] op_sel_hi:[1,1]
	v_pk_add_f32 v[222:223], v[222:223], v[200:201] op_sel:[0,1] op_sel_hi:[1,1]
	v_rcp_f32_e32 v216, v216
	v_rcp_f32_e32 v217, v217
	v_rcp_f32_e32 v218, v218
	v_rcp_f32_e32 v219, v219
	v_rcp_f32_e32 v220, v220
	v_rcp_f32_e32 v221, v221
	v_rcp_f32_e32 v222, v222
	v_rcp_f32_e32 v223, v223
	v_cvt_pk_bf16_f32 v240, v216, v217
	v_cvt_pk_bf16_f32 v241, v218, v219
	v_cvt_pk_bf16_f32 v242, v220, v221
	v_cvt_pk_bf16_f32 v243, v222, v223
	v_add_u32_e32 v128, 32, v198
	v_mad_i64_i32 v[128:129], s[36:37], s0, v128, 0
	v_lshl_add_u64 v[128:129], v[128:129], 1, v[164:165]
	s_cmp_gt_i32 s23, 1
	s_mov_b64 s[36:37], -1
	global_store_dwordx4 v[128:129], v[240:243], off nt
	s_mov_b64 s[36:37], 0
	s_andn2_b64 vcc, exec, s[36:37]
	v_pk_fma_f32 v[204:205], v[40:41], v[136:137], v[56:57] op_sel:[0,1,0]
	v_pk_fma_f32 v[206:207], v[42:43], v[136:137], v[58:59] op_sel:[0,1,0]
	v_pk_fma_f32 v[208:209], v[32:33], v[136:137], v[44:45] op_sel:[0,1,0]
	v_pk_fma_f32 v[210:211], v[34:35], v[136:137], v[46:47] op_sel:[0,1,0]
	v_pk_fma_f32 v[204:205], v[124:125], v[136:137], v[204:205] op_sel_hi:[1,0,1]
	v_pk_fma_f32 v[206:207], v[126:127], v[136:137], v[206:207] op_sel_hi:[1,0,1]
	v_pk_fma_f32 v[208:209], v[120:121], v[136:137], v[208:209] op_sel_hi:[1,0,1]
	v_pk_fma_f32 v[210:211], v[122:123], v[136:137], v[210:211] op_sel_hi:[1,0,1]
	v_pk_mul_f32 v[216:217], v[204:205], v[200:201] op_sel_hi:[1,0]
	v_pk_mul_f32 v[218:219], v[206:207], v[200:201] op_sel_hi:[1,0]
	v_pk_mul_f32 v[220:221], v[208:209], v[200:201] op_sel_hi:[1,0]
	v_pk_mul_f32 v[222:223], v[210:211], v[200:201] op_sel_hi:[1,0]
	v_exp_f32_e32 v216, v216
	v_exp_f32_e32 v217, v217
	v_exp_f32_e32 v218, v218
	v_exp_f32_e32 v219, v219
	v_exp_f32_e32 v220, v220
	v_exp_f32_e32 v221, v221
	v_exp_f32_e32 v222, v222
	v_exp_f32_e32 v223, v223
	v_pk_add_f32 v[216:217], v[216:217], v[200:201] op_sel:[0,1] op_sel_hi:[1,1]
	v_pk_add_f32 v[218:219], v[218:219], v[200:201] op_sel:[0,1] op_sel_hi:[1,1]
	v_pk_add_f32 v[220:221], v[220:221], v[200:201] op_sel:[0,1] op_sel_hi:[1,1]
	v_pk_add_f32 v[222:223], v[222:223], v[200:201] op_sel:[0,1] op_sel_hi:[1,1]
	v_rcp_f32_e32 v216, v216
	v_rcp_f32_e32 v217, v217
	v_rcp_f32_e32 v218, v218
	v_rcp_f32_e32 v219, v219
	v_rcp_f32_e32 v220, v220
	v_rcp_f32_e32 v221, v221
	v_rcp_f32_e32 v222, v222
	v_rcp_f32_e32 v223, v223
	v_cvt_pk_bf16_f32 v244, v216, v217
	v_cvt_pk_bf16_f32 v245, v218, v219
	v_cvt_pk_bf16_f32 v246, v220, v221
	v_cvt_pk_bf16_f32 v247, v222, v223
	global_store_dwordx4 v[128:129], v[244:247], off offset:256 nt
	s_cmp_gt_i32 s23, 1
	s_mov_b64 s[36:37], -1
	s_mov_b64 s[36:37], 0
	s_andn2_b64 vcc, exec, s[36:37]
	v_pk_fma_f32 v[204:205], v[68:69], v[138:139], v[72:73] op_sel:[0,1,0]
	v_pk_fma_f32 v[206:207], v[70:71], v[138:139], v[74:75] op_sel:[0,1,0]
	v_pk_fma_f32 v[208:209], v[60:61], v[138:139], v[64:65] op_sel:[0,1,0]
	v_pk_fma_f32 v[210:211], v[62:63], v[138:139], v[66:67] op_sel:[0,1,0]
	v_pk_fma_f32 v[204:205], v[116:117], v[138:139], v[204:205] op_sel_hi:[1,0,1]
	v_pk_fma_f32 v[206:207], v[118:119], v[138:139], v[206:207] op_sel_hi:[1,0,1]
	v_pk_fma_f32 v[208:209], v[112:113], v[138:139], v[208:209] op_sel_hi:[1,0,1]
	v_pk_fma_f32 v[210:211], v[114:115], v[138:139], v[210:211] op_sel_hi:[1,0,1]
	v_pk_mul_f32 v[216:217], v[204:205], v[200:201] op_sel_hi:[1,0]
	v_pk_mul_f32 v[218:219], v[206:207], v[200:201] op_sel_hi:[1,0]
	v_pk_mul_f32 v[220:221], v[208:209], v[200:201] op_sel_hi:[1,0]
	v_pk_mul_f32 v[222:223], v[210:211], v[200:201] op_sel_hi:[1,0]
	v_exp_f32_e32 v216, v216
	v_exp_f32_e32 v217, v217
	v_exp_f32_e32 v218, v218
	v_exp_f32_e32 v219, v219
	v_exp_f32_e32 v220, v220
	v_exp_f32_e32 v221, v221
	v_exp_f32_e32 v222, v222
	v_exp_f32_e32 v223, v223
	v_pk_add_f32 v[216:217], v[216:217], v[200:201] op_sel:[0,1] op_sel_hi:[1,1]
	v_pk_add_f32 v[218:219], v[218:219], v[200:201] op_sel:[0,1] op_sel_hi:[1,1]
	v_pk_add_f32 v[220:221], v[220:221], v[200:201] op_sel:[0,1] op_sel_hi:[1,1]
	v_pk_add_f32 v[222:223], v[222:223], v[200:201] op_sel:[0,1] op_sel_hi:[1,1]
	v_rcp_f32_e32 v216, v216
	v_rcp_f32_e32 v217, v217
	v_rcp_f32_e32 v218, v218
	v_rcp_f32_e32 v219, v219
	v_rcp_f32_e32 v220, v220
	v_rcp_f32_e32 v221, v221
	v_rcp_f32_e32 v222, v222
	v_rcp_f32_e32 v223, v223
	v_cvt_pk_bf16_f32 v248, v216, v217
	v_cvt_pk_bf16_f32 v249, v218, v219
	v_cvt_pk_bf16_f32 v250, v220, v221
	v_cvt_pk_bf16_f32 v251, v222, v223
	v_add_u32_e32 v112, 48, v198
	v_mad_i64_i32 v[112:113], s[36:37], s0, v112, 0
	v_lshl_add_u64 v[112:113], v[112:113], 1, v[164:165]
	global_store_dwordx4 v[112:113], v[248:251], off nt
	s_cmp_gt_i32 s23, 1
	s_mov_b64 s[36:37], -1
	s_mov_b64 s[36:37], 0
	s_andn2_b64 vcc, exec, s[36:37]
	v_pk_fma_f32 v[204:205], v[40:41], v[138:139], v[56:57] op_sel:[0,1,0]
	v_pk_fma_f32 v[206:207], v[42:43], v[138:139], v[58:59] op_sel:[0,1,0]
	v_pk_fma_f32 v[208:209], v[32:33], v[138:139], v[44:45] op_sel:[0,1,0]
	v_pk_fma_f32 v[210:211], v[34:35], v[138:139], v[46:47] op_sel:[0,1,0]
	v_pk_fma_f32 v[204:205], v[108:109], v[138:139], v[204:205] op_sel_hi:[1,0,1]
	v_pk_fma_f32 v[206:207], v[110:111], v[138:139], v[206:207] op_sel_hi:[1,0,1]
	v_pk_fma_f32 v[208:209], v[104:105], v[138:139], v[208:209] op_sel_hi:[1,0,1]
	v_pk_fma_f32 v[210:211], v[106:107], v[138:139], v[210:211] op_sel_hi:[1,0,1]
	v_pk_mul_f32 v[216:217], v[204:205], v[200:201] op_sel_hi:[1,0]
	v_pk_mul_f32 v[218:219], v[206:207], v[200:201] op_sel_hi:[1,0]
	v_pk_mul_f32 v[220:221], v[208:209], v[200:201] op_sel_hi:[1,0]
	v_pk_mul_f32 v[222:223], v[210:211], v[200:201] op_sel_hi:[1,0]
	v_exp_f32_e32 v216, v216
	v_exp_f32_e32 v217, v217
	v_exp_f32_e32 v218, v218
	v_exp_f32_e32 v219, v219
	v_exp_f32_e32 v220, v220
	v_exp_f32_e32 v221, v221
	v_exp_f32_e32 v222, v222
	v_exp_f32_e32 v223, v223
	v_pk_add_f32 v[216:217], v[216:217], v[200:201] op_sel:[0,1] op_sel_hi:[1,1]
	v_pk_add_f32 v[218:219], v[218:219], v[200:201] op_sel:[0,1] op_sel_hi:[1,1]
	v_pk_add_f32 v[220:221], v[220:221], v[200:201] op_sel:[0,1] op_sel_hi:[1,1]
	v_pk_add_f32 v[222:223], v[222:223], v[200:201] op_sel:[0,1] op_sel_hi:[1,1]
	v_rcp_f32_e32 v216, v216
	v_rcp_f32_e32 v217, v217
	v_rcp_f32_e32 v218, v218
	v_rcp_f32_e32 v219, v219
	v_rcp_f32_e32 v220, v220
	v_rcp_f32_e32 v221, v221
	v_rcp_f32_e32 v222, v222
	v_rcp_f32_e32 v223, v223
	v_cvt_pk_bf16_f32 v224, v216, v217
	v_cvt_pk_bf16_f32 v225, v218, v219
	v_cvt_pk_bf16_f32 v226, v220, v221
	v_cvt_pk_bf16_f32 v227, v222, v223
	global_store_dwordx4 v[112:113], v[224:227], off offset:256 nt
	s_cmp_gt_i32 s23, 1
	s_mov_b64 s[36:37], -1
	s_mov_b64 s[36:37], 0
	s_andn2_b64 vcc, exec, s[36:37]
	v_pk_fma_f32 v[204:205], v[68:69], v[100:101], v[72:73] op_sel:[0,1,0]
	v_pk_fma_f32 v[206:207], v[70:71], v[100:101], v[74:75] op_sel:[0,1,0]
	v_pk_fma_f32 v[208:209], v[60:61], v[100:101], v[64:65] op_sel:[0,1,0]
	v_pk_fma_f32 v[210:211], v[62:63], v[100:101], v[66:67] op_sel:[0,1,0]
	v_pk_fma_f32 v[204:205], v[96:97], v[100:101], v[204:205] op_sel_hi:[1,0,1]
	v_pk_fma_f32 v[206:207], v[98:99], v[100:101], v[206:207] op_sel_hi:[1,0,1]
	v_pk_fma_f32 v[208:209], v[92:93], v[100:101], v[208:209] op_sel_hi:[1,0,1]
	v_pk_fma_f32 v[210:211], v[94:95], v[100:101], v[210:211] op_sel_hi:[1,0,1]
	v_pk_mul_f32 v[216:217], v[204:205], v[200:201] op_sel_hi:[1,0]
	v_pk_mul_f32 v[218:219], v[206:207], v[200:201] op_sel_hi:[1,0]
	v_pk_mul_f32 v[220:221], v[208:209], v[200:201] op_sel_hi:[1,0]
	v_pk_mul_f32 v[222:223], v[210:211], v[200:201] op_sel_hi:[1,0]
	v_exp_f32_e32 v216, v216
	v_exp_f32_e32 v217, v217
	v_exp_f32_e32 v218, v218
	v_exp_f32_e32 v219, v219
	v_exp_f32_e32 v220, v220
	v_exp_f32_e32 v221, v221
	v_exp_f32_e32 v222, v222
	v_exp_f32_e32 v223, v223
	v_pk_add_f32 v[216:217], v[216:217], v[200:201] op_sel:[0,1] op_sel_hi:[1,1]
	v_pk_add_f32 v[218:219], v[218:219], v[200:201] op_sel:[0,1] op_sel_hi:[1,1]
	v_pk_add_f32 v[220:221], v[220:221], v[200:201] op_sel:[0,1] op_sel_hi:[1,1]
	v_pk_add_f32 v[222:223], v[222:223], v[200:201] op_sel:[0,1] op_sel_hi:[1,1]
	v_rcp_f32_e32 v216, v216
	v_rcp_f32_e32 v217, v217
	v_rcp_f32_e32 v218, v218
	v_rcp_f32_e32 v219, v219
	v_rcp_f32_e32 v220, v220
	v_rcp_f32_e32 v221, v221
	v_rcp_f32_e32 v222, v222
	v_rcp_f32_e32 v223, v223
	v_cvt_pk_bf16_f32 v228, v216, v217
	v_cvt_pk_bf16_f32 v229, v218, v219
	v_cvt_pk_bf16_f32 v230, v220, v221
	v_cvt_pk_bf16_f32 v231, v222, v223
	v_add_u32_e32 v92, 0x80, v198
	v_mad_i64_i32 v[92:93], s[36:37], s0, v92, 0
	v_lshl_add_u64 v[92:93], v[92:93], 1, v[164:165]
	s_cmp_gt_i32 s23, 1
	s_mov_b64 s[36:37], -1
	global_store_dwordx4 v[92:93], v[228:231], off nt
	s_mov_b64 s[36:37], 0
	s_andn2_b64 vcc, exec, s[36:37]
	v_pk_fma_f32 v[204:205], v[40:41], v[100:101], v[56:57] op_sel:[0,1,0]
	v_pk_fma_f32 v[206:207], v[42:43], v[100:101], v[58:59] op_sel:[0,1,0]
	v_pk_fma_f32 v[208:209], v[32:33], v[100:101], v[44:45] op_sel:[0,1,0]
	v_pk_fma_f32 v[210:211], v[34:35], v[100:101], v[46:47] op_sel:[0,1,0]
	v_pk_fma_f32 v[204:205], v[88:89], v[100:101], v[204:205] op_sel_hi:[1,0,1]
	v_pk_fma_f32 v[206:207], v[90:91], v[100:101], v[206:207] op_sel_hi:[1,0,1]
	v_pk_fma_f32 v[208:209], v[84:85], v[100:101], v[208:209] op_sel_hi:[1,0,1]
	v_pk_fma_f32 v[210:211], v[86:87], v[100:101], v[210:211] op_sel_hi:[1,0,1]
	v_pk_mul_f32 v[216:217], v[204:205], v[200:201] op_sel_hi:[1,0]
	v_pk_mul_f32 v[218:219], v[206:207], v[200:201] op_sel_hi:[1,0]
	v_pk_mul_f32 v[220:221], v[208:209], v[200:201] op_sel_hi:[1,0]
	v_pk_mul_f32 v[222:223], v[210:211], v[200:201] op_sel_hi:[1,0]
	v_exp_f32_e32 v216, v216
	v_exp_f32_e32 v217, v217
	v_exp_f32_e32 v218, v218
	v_exp_f32_e32 v219, v219
	v_exp_f32_e32 v220, v220
	v_exp_f32_e32 v221, v221
	v_exp_f32_e32 v222, v222
	v_exp_f32_e32 v223, v223
	v_pk_add_f32 v[216:217], v[216:217], v[200:201] op_sel:[0,1] op_sel_hi:[1,1]
	v_pk_add_f32 v[218:219], v[218:219], v[200:201] op_sel:[0,1] op_sel_hi:[1,1]
	v_pk_add_f32 v[220:221], v[220:221], v[200:201] op_sel:[0,1] op_sel_hi:[1,1]
	v_pk_add_f32 v[222:223], v[222:223], v[200:201] op_sel:[0,1] op_sel_hi:[1,1]
	v_rcp_f32_e32 v216, v216
	v_rcp_f32_e32 v217, v217
	v_rcp_f32_e32 v218, v218
	v_rcp_f32_e32 v219, v219
	v_rcp_f32_e32 v220, v220
	v_rcp_f32_e32 v221, v221
	v_rcp_f32_e32 v222, v222
	v_rcp_f32_e32 v223, v223
	v_cvt_pk_bf16_f32 v232, v216, v217
	v_cvt_pk_bf16_f32 v233, v218, v219
	v_cvt_pk_bf16_f32 v234, v220, v221
	v_cvt_pk_bf16_f32 v235, v222, v223
	global_store_dwordx4 v[92:93], v[232:235], off offset:256 nt
	s_cmp_gt_i32 s23, 1
	s_mov_b64 s[36:37], -1
	s_mov_b64 s[36:37], 0
	s_andn2_b64 vcc, exec, s[36:37]
	v_pk_fma_f32 v[204:205], v[68:69], v[102:103], v[72:73] op_sel:[0,1,0]
	v_pk_fma_f32 v[206:207], v[70:71], v[102:103], v[74:75] op_sel:[0,1,0]
	v_pk_fma_f32 v[208:209], v[60:61], v[102:103], v[64:65] op_sel:[0,1,0]
	v_pk_fma_f32 v[210:211], v[62:63], v[102:103], v[66:67] op_sel:[0,1,0]
	v_pk_fma_f32 v[204:205], v[80:81], v[102:103], v[204:205] op_sel_hi:[1,0,1]
	v_pk_fma_f32 v[206:207], v[82:83], v[102:103], v[206:207] op_sel_hi:[1,0,1]
	v_pk_fma_f32 v[208:209], v[76:77], v[102:103], v[208:209] op_sel_hi:[1,0,1]
	v_pk_fma_f32 v[210:211], v[78:79], v[102:103], v[210:211] op_sel_hi:[1,0,1]
	v_pk_mul_f32 v[216:217], v[204:205], v[200:201] op_sel_hi:[1,0]
	v_pk_mul_f32 v[218:219], v[206:207], v[200:201] op_sel_hi:[1,0]
	v_pk_mul_f32 v[220:221], v[208:209], v[200:201] op_sel_hi:[1,0]
	v_pk_mul_f32 v[222:223], v[210:211], v[200:201] op_sel_hi:[1,0]
	v_exp_f32_e32 v216, v216
	v_exp_f32_e32 v217, v217
	v_exp_f32_e32 v218, v218
	v_exp_f32_e32 v219, v219
	v_exp_f32_e32 v220, v220
	v_exp_f32_e32 v221, v221
	v_exp_f32_e32 v222, v222
	v_exp_f32_e32 v223, v223
	v_pk_add_f32 v[216:217], v[216:217], v[200:201] op_sel:[0,1] op_sel_hi:[1,1]
	v_pk_add_f32 v[218:219], v[218:219], v[200:201] op_sel:[0,1] op_sel_hi:[1,1]
	v_pk_add_f32 v[220:221], v[220:221], v[200:201] op_sel:[0,1] op_sel_hi:[1,1]
	v_pk_add_f32 v[222:223], v[222:223], v[200:201] op_sel:[0,1] op_sel_hi:[1,1]
	v_rcp_f32_e32 v216, v216
	v_rcp_f32_e32 v217, v217
	v_rcp_f32_e32 v218, v218
	v_rcp_f32_e32 v219, v219
	v_rcp_f32_e32 v220, v220
	v_rcp_f32_e32 v221, v221
	v_rcp_f32_e32 v222, v222
	v_rcp_f32_e32 v223, v223
	v_cvt_pk_bf16_f32 v236, v216, v217
	v_cvt_pk_bf16_f32 v237, v218, v219
	v_cvt_pk_bf16_f32 v238, v220, v221
	v_cvt_pk_bf16_f32 v239, v222, v223
	v_add_u32_e32 v76, 0x90, v198
	v_mad_i64_i32 v[76:77], s[36:37], s0, v76, 0
	v_lshl_add_u64 v[76:77], v[76:77], 1, v[164:165]
	global_store_dwordx4 v[76:77], v[236:239], off nt
	s_cmp_gt_i32 s23, 1
	s_mov_b64 s[36:37], -1
	s_mov_b64 s[36:37], 0
	s_andn2_b64 vcc, exec, s[36:37]
	v_pk_fma_f32 v[204:205], v[40:41], v[102:103], v[56:57] op_sel:[0,1,0]
	v_pk_fma_f32 v[206:207], v[42:43], v[102:103], v[58:59] op_sel:[0,1,0]
	v_pk_fma_f32 v[208:209], v[32:33], v[102:103], v[44:45] op_sel:[0,1,0]
	v_pk_fma_f32 v[210:211], v[34:35], v[102:103], v[46:47] op_sel:[0,1,0]
	v_pk_fma_f32 v[204:205], v[52:53], v[102:103], v[204:205] op_sel_hi:[1,0,1]
	v_pk_fma_f32 v[206:207], v[54:55], v[102:103], v[206:207] op_sel_hi:[1,0,1]
	v_pk_fma_f32 v[208:209], v[36:37], v[102:103], v[208:209] op_sel_hi:[1,0,1]
	v_pk_fma_f32 v[210:211], v[38:39], v[102:103], v[210:211] op_sel_hi:[1,0,1]
	v_pk_mul_f32 v[216:217], v[204:205], v[200:201] op_sel_hi:[1,0]
	v_pk_mul_f32 v[218:219], v[206:207], v[200:201] op_sel_hi:[1,0]
	v_pk_mul_f32 v[220:221], v[208:209], v[200:201] op_sel_hi:[1,0]
	v_pk_mul_f32 v[222:223], v[210:211], v[200:201] op_sel_hi:[1,0]
	v_exp_f32_e32 v216, v216
	v_exp_f32_e32 v217, v217
	v_exp_f32_e32 v218, v218
	v_exp_f32_e32 v219, v219
	v_exp_f32_e32 v220, v220
	v_exp_f32_e32 v221, v221
	v_exp_f32_e32 v222, v222
	v_exp_f32_e32 v223, v223
	v_pk_add_f32 v[216:217], v[216:217], v[200:201] op_sel:[0,1] op_sel_hi:[1,1]
	v_pk_add_f32 v[218:219], v[218:219], v[200:201] op_sel:[0,1] op_sel_hi:[1,1]
	v_pk_add_f32 v[220:221], v[220:221], v[200:201] op_sel:[0,1] op_sel_hi:[1,1]
	v_pk_add_f32 v[222:223], v[222:223], v[200:201] op_sel:[0,1] op_sel_hi:[1,1]
	v_rcp_f32_e32 v216, v216
	v_rcp_f32_e32 v217, v217
	v_rcp_f32_e32 v218, v218
	v_rcp_f32_e32 v219, v219
	v_rcp_f32_e32 v220, v220
	v_rcp_f32_e32 v221, v221
	v_rcp_f32_e32 v222, v222
	v_rcp_f32_e32 v223, v223
	v_cvt_pk_bf16_f32 v240, v216, v217
	v_cvt_pk_bf16_f32 v241, v218, v219
	v_cvt_pk_bf16_f32 v242, v220, v221
	v_cvt_pk_bf16_f32 v243, v222, v223
	global_store_dwordx4 v[76:77], v[240:243], off offset:256 nt
	s_cmp_gt_i32 s23, 1
	s_mov_b64 s[36:37], -1
	s_mov_b64 s[36:37], 0
	s_andn2_b64 vcc, exec, s[36:37]
	v_pk_fma_f32 v[204:205], v[68:69], v[48:49], v[72:73] op_sel:[0,1,0]
	v_pk_fma_f32 v[206:207], v[70:71], v[48:49], v[74:75] op_sel:[0,1,0]
	v_pk_fma_f32 v[208:209], v[60:61], v[48:49], v[64:65] op_sel:[0,1,0]
	v_pk_fma_f32 v[210:211], v[62:63], v[48:49], v[66:67] op_sel:[0,1,0]
	v_pk_fma_f32 v[204:205], v[28:29], v[48:49], v[204:205] op_sel_hi:[1,0,1]
	v_pk_fma_f32 v[206:207], v[30:31], v[48:49], v[206:207] op_sel_hi:[1,0,1]
	v_pk_fma_f32 v[208:209], v[24:25], v[48:49], v[208:209] op_sel_hi:[1,0,1]
	v_pk_fma_f32 v[210:211], v[26:27], v[48:49], v[210:211] op_sel_hi:[1,0,1]
	v_pk_mul_f32 v[216:217], v[204:205], v[200:201] op_sel_hi:[1,0]
	v_pk_mul_f32 v[218:219], v[206:207], v[200:201] op_sel_hi:[1,0]
	v_pk_mul_f32 v[220:221], v[208:209], v[200:201] op_sel_hi:[1,0]
	v_pk_mul_f32 v[222:223], v[210:211], v[200:201] op_sel_hi:[1,0]
	v_exp_f32_e32 v216, v216
	v_exp_f32_e32 v217, v217
	v_exp_f32_e32 v218, v218
	v_exp_f32_e32 v219, v219
	v_exp_f32_e32 v220, v220
	v_exp_f32_e32 v221, v221
	v_exp_f32_e32 v222, v222
	v_exp_f32_e32 v223, v223
	v_pk_add_f32 v[216:217], v[216:217], v[200:201] op_sel:[0,1] op_sel_hi:[1,1]
	v_pk_add_f32 v[218:219], v[218:219], v[200:201] op_sel:[0,1] op_sel_hi:[1,1]
	v_pk_add_f32 v[220:221], v[220:221], v[200:201] op_sel:[0,1] op_sel_hi:[1,1]
	v_pk_add_f32 v[222:223], v[222:223], v[200:201] op_sel:[0,1] op_sel_hi:[1,1]
	v_rcp_f32_e32 v216, v216
	v_rcp_f32_e32 v217, v217
	v_rcp_f32_e32 v218, v218
	v_rcp_f32_e32 v219, v219
	v_rcp_f32_e32 v220, v220
	v_rcp_f32_e32 v221, v221
	v_rcp_f32_e32 v222, v222
	v_rcp_f32_e32 v223, v223
	v_cvt_pk_bf16_f32 v244, v216, v217
	v_cvt_pk_bf16_f32 v245, v218, v219
	v_cvt_pk_bf16_f32 v246, v220, v221
	v_cvt_pk_bf16_f32 v247, v222, v223
	v_add_u32_e32 v24, 0xa0, v198
	v_mad_i64_i32 v[24:25], s[36:37], s0, v24, 0
	v_lshl_add_u64 v[24:25], v[24:25], 1, v[164:165]
	s_cmp_gt_i32 s23, 1
	s_mov_b64 s[36:37], -1
	global_store_dwordx4 v[24:25], v[244:247], off nt
	s_mov_b64 s[36:37], 0
	s_andn2_b64 vcc, exec, s[36:37]
	v_pk_fma_f32 v[204:205], v[40:41], v[48:49], v[56:57] op_sel:[0,1,0]
	v_pk_fma_f32 v[206:207], v[42:43], v[48:49], v[58:59] op_sel:[0,1,0]
	v_pk_fma_f32 v[208:209], v[32:33], v[48:49], v[44:45] op_sel:[0,1,0]
	v_pk_fma_f32 v[210:211], v[34:35], v[48:49], v[46:47] op_sel:[0,1,0]
	v_pk_fma_f32 v[204:205], v[20:21], v[48:49], v[204:205] op_sel_hi:[1,0,1]
	v_pk_fma_f32 v[206:207], v[22:23], v[48:49], v[206:207] op_sel_hi:[1,0,1]
	v_pk_fma_f32 v[208:209], v[16:17], v[48:49], v[208:209] op_sel_hi:[1,0,1]
	v_pk_fma_f32 v[210:211], v[18:19], v[48:49], v[210:211] op_sel_hi:[1,0,1]
	v_pk_mul_f32 v[216:217], v[204:205], v[200:201] op_sel_hi:[1,0]
	v_pk_mul_f32 v[218:219], v[206:207], v[200:201] op_sel_hi:[1,0]
	v_pk_mul_f32 v[220:221], v[208:209], v[200:201] op_sel_hi:[1,0]
	v_pk_mul_f32 v[222:223], v[210:211], v[200:201] op_sel_hi:[1,0]
	v_exp_f32_e32 v216, v216
	v_exp_f32_e32 v217, v217
	v_exp_f32_e32 v218, v218
	v_exp_f32_e32 v219, v219
	v_exp_f32_e32 v220, v220
	v_exp_f32_e32 v221, v221
	v_exp_f32_e32 v222, v222
	v_exp_f32_e32 v223, v223
	v_pk_add_f32 v[216:217], v[216:217], v[200:201] op_sel:[0,1] op_sel_hi:[1,1]
	v_pk_add_f32 v[218:219], v[218:219], v[200:201] op_sel:[0,1] op_sel_hi:[1,1]
	v_pk_add_f32 v[220:221], v[220:221], v[200:201] op_sel:[0,1] op_sel_hi:[1,1]
	v_pk_add_f32 v[222:223], v[222:223], v[200:201] op_sel:[0,1] op_sel_hi:[1,1]
	v_rcp_f32_e32 v216, v216
	v_rcp_f32_e32 v217, v217
	v_rcp_f32_e32 v218, v218
	v_rcp_f32_e32 v219, v219
	v_rcp_f32_e32 v220, v220
	v_rcp_f32_e32 v221, v221
	v_rcp_f32_e32 v222, v222
	v_rcp_f32_e32 v223, v223
	v_cvt_pk_bf16_f32 v248, v216, v217
	v_cvt_pk_bf16_f32 v249, v218, v219
	v_cvt_pk_bf16_f32 v250, v220, v221
	v_cvt_pk_bf16_f32 v251, v222, v223
	global_store_dwordx4 v[24:25], v[248:251], off offset:256 nt
	s_cmp_gt_i32 s23, 1
	s_mov_b64 s[36:37], -1
	s_mov_b64 s[36:37], 0
	s_andn2_b64 vcc, exec, s[36:37]
	v_pk_fma_f32 v[204:205], v[68:69], v[50:51], v[72:73] op_sel:[0,1,0]
	v_pk_fma_f32 v[206:207], v[70:71], v[50:51], v[74:75] op_sel:[0,1,0]
	v_pk_fma_f32 v[208:209], v[60:61], v[50:51], v[64:65] op_sel:[0,1,0]
	v_pk_fma_f32 v[210:211], v[62:63], v[50:51], v[66:67] op_sel:[0,1,0]
	v_pk_fma_f32 v[204:205], v[12:13], v[50:51], v[204:205] op_sel_hi:[1,0,1]
	v_pk_fma_f32 v[206:207], v[14:15], v[50:51], v[206:207] op_sel_hi:[1,0,1]
	v_pk_fma_f32 v[208:209], v[8:9], v[50:51], v[208:209] op_sel_hi:[1,0,1]
	v_pk_fma_f32 v[210:211], v[10:11], v[50:51], v[210:211] op_sel_hi:[1,0,1]
	v_pk_mul_f32 v[216:217], v[204:205], v[200:201] op_sel_hi:[1,0]
	v_pk_mul_f32 v[218:219], v[206:207], v[200:201] op_sel_hi:[1,0]
	v_pk_mul_f32 v[220:221], v[208:209], v[200:201] op_sel_hi:[1,0]
	v_pk_mul_f32 v[222:223], v[210:211], v[200:201] op_sel_hi:[1,0]
	v_exp_f32_e32 v216, v216
	v_exp_f32_e32 v217, v217
	v_exp_f32_e32 v218, v218
	v_exp_f32_e32 v219, v219
	v_exp_f32_e32 v220, v220
	v_exp_f32_e32 v221, v221
	v_exp_f32_e32 v222, v222
	v_exp_f32_e32 v223, v223
	v_pk_add_f32 v[216:217], v[216:217], v[200:201] op_sel:[0,1] op_sel_hi:[1,1]
	v_pk_add_f32 v[218:219], v[218:219], v[200:201] op_sel:[0,1] op_sel_hi:[1,1]
	v_pk_add_f32 v[220:221], v[220:221], v[200:201] op_sel:[0,1] op_sel_hi:[1,1]
	v_pk_add_f32 v[222:223], v[222:223], v[200:201] op_sel:[0,1] op_sel_hi:[1,1]
	v_rcp_f32_e32 v216, v216
	v_rcp_f32_e32 v217, v217
	v_rcp_f32_e32 v218, v218
	v_rcp_f32_e32 v219, v219
	v_rcp_f32_e32 v220, v220
	v_rcp_f32_e32 v221, v221
	v_rcp_f32_e32 v222, v222
	v_rcp_f32_e32 v223, v223
	v_cvt_pk_bf16_f32 v224, v216, v217
	v_cvt_pk_bf16_f32 v225, v218, v219
	v_cvt_pk_bf16_f32 v226, v220, v221
	v_cvt_pk_bf16_f32 v227, v222, v223
	v_add_u32_e32 v8, 0xb0, v198
	v_mad_i64_i32 v[8:9], s[36:37], s0, v8, 0
	v_lshl_add_u64 v[8:9], v[8:9], 1, v[164:165]
	global_store_dwordx4 v[8:9], v[224:227], off nt
	s_cmp_gt_i32 s23, 1
	s_mov_b64 s[36:37], -1
	s_mov_b64 s[36:37], 0
	s_andn2_b64 vcc, exec, s[36:37]
	s_andn2_b64 vcc, exec, s[10:11]
	s_mov_b64 s[10:11], -1
	v_pk_fma_f32 v[204:205], v[40:41], v[50:51], v[56:57] op_sel:[0,1,0]
	v_pk_fma_f32 v[206:207], v[42:43], v[50:51], v[58:59] op_sel:[0,1,0]
	v_pk_fma_f32 v[208:209], v[32:33], v[50:51], v[44:45] op_sel:[0,1,0]
	v_pk_fma_f32 v[210:211], v[34:35], v[50:51], v[46:47] op_sel:[0,1,0]
	v_pk_fma_f32 v[204:205], v[4:5], v[50:51], v[204:205] op_sel_hi:[1,0,1]
	v_pk_fma_f32 v[206:207], v[6:7], v[50:51], v[206:207] op_sel_hi:[1,0,1]
	v_pk_fma_f32 v[208:209], v[0:1], v[50:51], v[208:209] op_sel_hi:[1,0,1]
	v_pk_fma_f32 v[210:211], v[2:3], v[50:51], v[210:211] op_sel_hi:[1,0,1]
	v_pk_mul_f32 v[216:217], v[204:205], v[200:201] op_sel_hi:[1,0]
	v_pk_mul_f32 v[218:219], v[206:207], v[200:201] op_sel_hi:[1,0]
	v_pk_mul_f32 v[220:221], v[208:209], v[200:201] op_sel_hi:[1,0]
	v_pk_mul_f32 v[222:223], v[210:211], v[200:201] op_sel_hi:[1,0]
	v_exp_f32_e32 v216, v216
	v_exp_f32_e32 v217, v217
	v_exp_f32_e32 v218, v218
	v_exp_f32_e32 v219, v219
	v_exp_f32_e32 v220, v220
	v_exp_f32_e32 v221, v221
	v_exp_f32_e32 v222, v222
	v_exp_f32_e32 v223, v223
	v_pk_add_f32 v[216:217], v[216:217], v[200:201] op_sel:[0,1] op_sel_hi:[1,1]
	v_pk_add_f32 v[218:219], v[218:219], v[200:201] op_sel:[0,1] op_sel_hi:[1,1]
	v_pk_add_f32 v[220:221], v[220:221], v[200:201] op_sel:[0,1] op_sel_hi:[1,1]
	v_pk_add_f32 v[222:223], v[222:223], v[200:201] op_sel:[0,1] op_sel_hi:[1,1]
	v_rcp_f32_e32 v216, v216
	v_rcp_f32_e32 v217, v217
	v_rcp_f32_e32 v218, v218
	v_rcp_f32_e32 v219, v219
	v_rcp_f32_e32 v220, v220
	v_rcp_f32_e32 v221, v221
	v_rcp_f32_e32 v222, v222
	v_rcp_f32_e32 v223, v223
	v_cvt_pk_bf16_f32 v228, v216, v217
	v_cvt_pk_bf16_f32 v229, v218, v219
	v_cvt_pk_bf16_f32 v230, v220, v221
	v_cvt_pk_bf16_f32 v231, v222, v223
	global_store_dwordx4 v[8:9], v[228:231], off offset:256 nt
